# in-proj epilogue: adjacent scalar f32 mul/add pairs packed into v_pk_mul_f32 / v_pk_add_f32 (224 pairs), bit-identical
# baseline (speedup 1.0000x reference)
; #define PG8_STAGE(bufoff, gbase, voff) do { _Pragma("unroll") for (int _i = 0; _i < 2; ++_i) \
;         __builtin_amdgcn_global_load_lds((const unsigned*)((const char*)(gbase) + (voff)[_i]), (LAS unsigned*)(lds + (bufoff) + ldsw + _i * 8192), 16, 0, 0); } while (0)
; #define PG8_LDA(dst, b, h) do { _Pragma("unroll") for (int m = 0; m < 4; ++m) _Pragma("unroll") for (int k = 0; k < 2; ++k) dst[m][k] = *(const LAS bf16x8*)(lds + PG8_SA(b, h) + aoff + m * 2048 + k * 1024); } while (0)
; #define PG8_WAIT_V(n) asm volatile("s_waitcnt vmcnt(" #n ")" ::: "memory")
; #define PG8_WAIT_L(n) asm volatile("s_waitcnt lgkmcnt(" #n ")" ::: "memory")
; template <class Prog>
; __device__ __forceinline__ void gemm_phase(LAS unsigned char* lds, const int K, const Prog& S) {
;     ...
;         for (int t = 0; t < nt; t += 2) {
;             const bool last = (t == nt - 2);
;             const char* a1 = cA + (size_t)(t + 1) * kstep;
;             const char* a2 = last ? nA : cA + (size_t)(t + 2) * kstep; const char* b2 = last ? nB : cB + (size_t)(t + 2) * kstep;
;             const char* a3 = a2 + kstep; const char* b3 = b2 + kstep;
;             PG8_LDB(B0, 0, 0); PG8_SCHED; PG8_LDA(At, 0, 0); PG8_STAGE(PG8_SA(1, 1), a1 + hstep, voffA);
;             PG8_WAIT_L(8); PG8_BAR; PG8_WAIT_L(0); PG8_MMA(0, 0, At, B0); PG8_BAR; PG8_SCHED;
;             PG8_LDB(B1, 0, 1); PG8_STAGE(PG8_SB(0, 0), b2, voffB);
;             PG8_BAR; PG8_WAIT_L(0); PG8_MMA(0, 1, At, B1); PG8_BAR;
;             PG8_LDA(At, 0, 1); PG8_STAGE(PG8_SA(0, 0), a2, voffA);
;             PG8_BAR; PG8_WAIT_L(0); PG8_MMA(1, 0, At, B0); PG8_BAR; PG8_SCHED;
;             PG8_STAGE(PG8_SB(0, 1), b2 + hstep, voffB);
;             PG8_WAIT_V(6); PG8_BAR; PG8_MMA(1, 1, At, B1); PG8_BAR;
;             PG8_LDB(B0, 1, 0); PG8_SCHED; PG8_LDA(At, 1, 0); PG8_STAGE(PG8_SA(0, 1), a2 + hstep, voffA);
;             PG8_WAIT_L(8); PG8_BAR; PG8_WAIT_L(0); PG8_MMA(0, 0, At, B0); PG8_BAR; PG8_SCHED;
;             PG8_LDB(B1, 1, 1); PG8_STAGE(PG8_SB(1, 0), b3, voffB);
;             PG8_BAR; PG8_WAIT_L(0); PG8_MMA(0, 1, At, B1); PG8_BAR;
;             PG8_LDA(At, 1, 1); PG8_STAGE(PG8_SA(1, 0), a3, voffA);
;             PG8_BAR; PG8_WAIT_L(0); PG8_MMA(1, 0, At, B0); PG8_BAR; PG8_SCHED;
;             PG8_STAGE(PG8_SB(1, 1), b3 + hstep, voffB);
;             PG8_WAIT_V(6); PG8_BAR; PG8_MMA(1, 1, At, B1); PG8_BAR;
.LBB0_101:
	s_add_u32 s44, s40, 0xfff80080
	s_addc_u32 s45, s41, -1
	s_cmp_eq_u32 s69, 28
	s_cselect_b32 s47, s5, s45
	s_cselect_b32 s46, s4, s44
	s_cselect_b32 s45, s13, s15
	s_cselect_b32 s44, s12, s9
	s_add_u32 s76, s40, 0xfff80000
	s_addc_u32 s77, s41, -1
	ds_read_b128 v[128:131], v244
	ds_read_b128 v[132:135], v244 offset:1024
	ds_read_b128 v[136:139], v244 offset:2048
	ds_read_b128 v[140:143], v244 offset:3072
	s_add_i32 m0, s92, 0x8000
	ds_read_b128 v[188:191], v244 offset:16384
	ds_read_b128 v[196:199], v244 offset:17408
	ds_read_b128 v[200:203], v244 offset:18432
	ds_read_b128 v[218:221], v244 offset:19456
	global_load_lds_dwordx4 v184, s[76:77]
	s_add_i32 m0, s92, 0xa000
	ds_read_b128 v[144:147], v216
	ds_read_b128 v[148:151], v216 offset:1024
	ds_read_b128 v[152:155], v216 offset:2048
	ds_read_b128 v[156:159], v216 offset:3072
	global_load_lds_dwordx4 v186, s[76:77]
	s_add_i32 m0, s92, 0xc000
	ds_read_b128 v[160:163], v216 offset:4096
	ds_read_b128 v[164:167], v216 offset:5120
	ds_read_b128 v[168:171], v216 offset:6144
	ds_read_b128 v[172:175], v216 offset:7168
	global_load_lds_dwordx4 v184, s[40:41]
	s_add_i32 m0, s92, 0xe000
	s_nop 0
	global_load_lds_dwordx4 v186, s[40:41]
	s_waitcnt lgkmcnt(0)
	s_barrier
	v_mfma_f32_16x16x32_bf16 v[124:127], v[128:131], v[144:147], v[124:127]
	v_mfma_f32_16x16x32_bf16 v[116:119], v[136:139], v[144:147], v[116:119]
	v_mfma_f32_16x16x32_bf16 v[108:111], v[128:131], v[152:155], v[108:111]
	v_mfma_f32_16x16x32_bf16 v[100:103], v[136:139], v[152:155], v[100:103]
	v_mfma_f32_16x16x32_bf16 v[92:95], v[128:131], v[160:163], v[92:95]
	v_mfma_f32_16x16x32_bf16 v[84:87], v[136:139], v[160:163], v[84:87]
	v_mfma_f32_16x16x32_bf16 v[76:79], v[128:131], v[168:171], v[76:79]
	v_mfma_f32_16x16x32_bf16 v[68:71], v[136:139], v[168:171], v[68:71]
	v_mfma_f32_16x16x32_bf16 v[124:127], v[132:135], v[148:151], v[124:127]
	v_mfma_f32_16x16x32_bf16 v[116:119], v[140:143], v[148:151], v[116:119]
	v_mfma_f32_16x16x32_bf16 v[108:111], v[132:135], v[156:159], v[108:111]
	v_mfma_f32_16x16x32_bf16 v[100:103], v[140:143], v[156:159], v[100:103]
	v_mfma_f32_16x16x32_bf16 v[92:95], v[132:135], v[164:167], v[92:95]
	v_mfma_f32_16x16x32_bf16 v[84:87], v[140:143], v[164:167], v[84:87]
	v_mfma_f32_16x16x32_bf16 v[76:79], v[132:135], v[172:175], v[76:79]
	v_mfma_f32_16x16x32_bf16 v[68:71], v[140:143], v[172:175], v[68:71]
	v_mfma_f32_16x16x32_bf16 v[120:123], v[188:191], v[144:147], v[120:123]
	v_mfma_f32_16x16x32_bf16 v[112:115], v[200:203], v[144:147], v[112:115]
	v_mfma_f32_16x16x32_bf16 v[104:107], v[188:191], v[152:155], v[104:107]
	v_mfma_f32_16x16x32_bf16 v[96:99], v[200:203], v[152:155], v[96:99]
	v_mfma_f32_16x16x32_bf16 v[88:91], v[188:191], v[160:163], v[88:91]
	v_mfma_f32_16x16x32_bf16 v[80:83], v[200:203], v[160:163], v[80:83]
	v_mfma_f32_16x16x32_bf16 v[72:75], v[188:191], v[168:171], v[72:75]
	v_mfma_f32_16x16x32_bf16 v[64:67], v[200:203], v[168:171], v[64:67]
	v_mfma_f32_16x16x32_bf16 v[120:123], v[196:199], v[148:151], v[120:123]
	v_mfma_f32_16x16x32_bf16 v[112:115], v[218:221], v[148:151], v[112:115]
	v_mfma_f32_16x16x32_bf16 v[104:107], v[196:199], v[156:159], v[104:107]
	v_mfma_f32_16x16x32_bf16 v[96:99], v[218:221], v[156:159], v[96:99]
	v_mfma_f32_16x16x32_bf16 v[88:91], v[196:199], v[164:167], v[88:91]
	v_mfma_f32_16x16x32_bf16 v[80:83], v[218:221], v[164:167], v[80:83]
	v_mfma_f32_16x16x32_bf16 v[72:75], v[196:199], v[172:175], v[72:75]
	v_mfma_f32_16x16x32_bf16 v[64:67], v[218:221], v[172:175], v[64:67]
	s_barrier
	ds_read_b128 v[144:147], v216 offset:16384
	ds_read_b128 v[148:151], v216 offset:17408
	ds_read_b128 v[152:155], v216 offset:18432
	ds_read_b128 v[156:159], v216 offset:19456
	s_add_i32 m0, s92, 0x10000
	ds_read_b128 v[160:163], v216 offset:20480
	ds_read_b128 v[164:167], v216 offset:21504
	ds_read_b128 v[168:171], v216 offset:22528
	ds_read_b128 v[172:175], v216 offset:23552
	global_load_lds_dwordx4 v192, s[44:45]
	s_add_i32 m0, s92, 0x12000
	s_nop 0
	global_load_lds_dwordx4 v180, s[44:45]
	s_add_u32 s76, s44, 0x80000
	s_addc_u32 s77, s45, 0
	s_add_i32 m0, s92, 0x14000
	s_nop 0
	global_load_lds_dwordx4 v192, s[76:77]
	s_add_i32 m0, s92, 0x16000
	s_nop 0
	global_load_lds_dwordx4 v180, s[76:77]
	s_waitcnt vmcnt(4)
	s_waitcnt lgkmcnt(0)
	s_barrier
	v_mfma_f32_16x16x32_bf16 v[60:63], v[128:131], v[144:147], v[60:63]
	v_mfma_f32_16x16x32_bf16 v[52:55], v[136:139], v[144:147], v[52:55]
	v_mfma_f32_16x16x32_bf16 v[44:47], v[128:131], v[152:155], v[44:47]
	v_mfma_f32_16x16x32_bf16 v[36:39], v[136:139], v[152:155], v[36:39]
	v_mfma_f32_16x16x32_bf16 v[28:31], v[128:131], v[160:163], v[28:31]
	v_mfma_f32_16x16x32_bf16 v[20:23], v[136:139], v[160:163], v[20:23]
	v_mfma_f32_16x16x32_bf16 v[12:15], v[128:131], v[168:171], v[12:15]
	v_mfma_f32_16x16x32_bf16 v[4:7], v[136:139], v[168:171], v[4:7]
	v_mfma_f32_16x16x32_bf16 v[60:63], v[132:135], v[148:151], v[60:63]
	v_mfma_f32_16x16x32_bf16 v[52:55], v[140:143], v[148:151], v[52:55]
	v_mfma_f32_16x16x32_bf16 v[44:47], v[132:135], v[156:159], v[44:47]
	v_mfma_f32_16x16x32_bf16 v[36:39], v[140:143], v[156:159], v[36:39]
	v_mfma_f32_16x16x32_bf16 v[28:31], v[132:135], v[164:167], v[28:31]
	v_mfma_f32_16x16x32_bf16 v[20:23], v[140:143], v[164:167], v[20:23]
	v_mfma_f32_16x16x32_bf16 v[12:15], v[132:135], v[172:175], v[12:15]
	v_mfma_f32_16x16x32_bf16 v[4:7], v[140:143], v[172:175], v[4:7]
	v_mfma_f32_16x16x32_bf16 v[56:59], v[188:191], v[144:147], v[56:59]
	v_mfma_f32_16x16x32_bf16 v[48:51], v[200:203], v[144:147], v[48:51]
	v_mfma_f32_16x16x32_bf16 v[40:43], v[188:191], v[152:155], v[40:43]
	v_mfma_f32_16x16x32_bf16 v[32:35], v[200:203], v[152:155], v[32:35]
	v_mfma_f32_16x16x32_bf16 v[24:27], v[188:191], v[160:163], v[24:27]
	v_mfma_f32_16x16x32_bf16 v[16:19], v[200:203], v[160:163], v[16:19]
	v_mfma_f32_16x16x32_bf16 v[8:11], v[188:191], v[168:171], v[8:11]
	v_mfma_f32_16x16x32_bf16 v[0:3], v[200:203], v[168:171], v[0:3]
	v_mfma_f32_16x16x32_bf16 v[56:59], v[196:199], v[148:151], v[56:59]
	v_mfma_f32_16x16x32_bf16 v[48:51], v[218:221], v[148:151], v[48:51]
	v_mfma_f32_16x16x32_bf16 v[40:43], v[196:199], v[156:159], v[40:43]
	v_mfma_f32_16x16x32_bf16 v[32:35], v[218:221], v[156:159], v[32:35]
	v_mfma_f32_16x16x32_bf16 v[24:27], v[196:199], v[164:167], v[24:27]
	v_mfma_f32_16x16x32_bf16 v[16:19], v[218:221], v[164:167], v[16:19]
	v_mfma_f32_16x16x32_bf16 v[8:11], v[196:199], v[172:175], v[8:11]
	v_mfma_f32_16x16x32_bf16 v[0:3], v[218:221], v[172:175], v[0:3]
	s_barrier
; #define PG8_STAGE(bufoff, gbase, voff) do { _Pragma("unroll") for (int _i = 0; _i < 2; ++_i) \
;         __builtin_amdgcn_global_load_lds((const unsigned*)((const char*)(gbase) + (voff)[_i]), (LAS unsigned*)(lds + (bufoff) + ldsw + _i * 8192), 16, 0, 0); } while (0)
; #define PG8_WAIT_V(n) asm volatile("s_waitcnt vmcnt(" #n ")" ::: "memory")
; template <class Prog>
; __device__ __forceinline__ void gemm_phase(LAS unsigned char* lds, const int K, const Prog& S) {
;     ...
;         for (int t = 0; t < nt; t += 2) {
;             const bool last = (t == nt - 2);
;             const char* a1 = cA + (size_t)(t + 1) * kstep;
;             const char* a2 = last ? nA : cA + (size_t)(t + 2) * kstep; const char* b2 = last ? nB : cB + (size_t)(t + 2) * kstep;
;             const char* a3 = a2 + kstep; const char* b3 = b2 + kstep;
;             PG8_LDB(B0, 0, 0); PG8_SCHED; PG8_LDA(At, 0, 0); PG8_STAGE(PG8_SA(1, 1), a1 + hstep, voffA);
;             PG8_WAIT_L(8); PG8_BAR; PG8_WAIT_L(0); PG8_MMA(0, 0, At, B0); PG8_BAR; PG8_SCHED;
;             PG8_LDB(B1, 0, 1); PG8_STAGE(PG8_SB(0, 0), b2, voffB);
;             PG8_BAR; PG8_WAIT_L(0); PG8_MMA(0, 1, At, B1); PG8_BAR;
;             PG8_LDA(At, 0, 1); PG8_STAGE(PG8_SA(0, 0), a2, voffA);
;             PG8_BAR; PG8_WAIT_L(0); PG8_MMA(1, 0, At, B0); PG8_BAR; PG8_SCHED;
;             PG8_STAGE(PG8_SB(0, 1), b2 + hstep, voffB);
;             PG8_WAIT_V(6); PG8_BAR; PG8_MMA(1, 1, At, B1); PG8_BAR;
;             PG8_LDB(B0, 1, 0); PG8_SCHED; PG8_LDA(At, 1, 0); PG8_STAGE(PG8_SA(0, 1), a2 + hstep, voffA);
;             PG8_WAIT_L(8); PG8_BAR; PG8_WAIT_L(0); PG8_MMA(0, 0, At, B0); PG8_BAR; PG8_SCHED;
;             PG8_LDB(B1, 1, 1); PG8_STAGE(PG8_SB(1, 0), b3, voffB);
;             PG8_BAR; PG8_WAIT_L(0); PG8_MMA(0, 1, At, B1); PG8_BAR;
;             PG8_LDA(At, 1, 1); PG8_STAGE(PG8_SA(1, 0), a3, voffA);
;             PG8_BAR; PG8_WAIT_L(0); PG8_MMA(1, 0, At, B0); PG8_BAR; PG8_SCHED;
;             PG8_STAGE(PG8_SB(1, 1), b3 + hstep, voffB);
;             PG8_WAIT_V(6); PG8_BAR; PG8_MMA(1, 1, At, B1); PG8_BAR;
;     __device__ __forceinline__ void epi(f32x4 (&acc)[2][2][4][2], const pg8::Unit& u, int wr, int wc, int fr, int fq) const {
;     ...
;         const int pn = u.pn;
;         const int mode = (pn < 8) ? 1 : ((pn >= 12 && pn < 16) || (pn >= 20 && pn < 24) || (pn >= 30 && pn < 34)) ? 2 : (pn >= 34 ? 3 : 0);
	s_add_u32 s76, s46, 0x80000
	s_addc_u32 s77, s47, 0
	ds_read_b128 v[128:131], v244 offset:32768
	ds_read_b128 v[132:135], v244 offset:33792
	ds_read_b128 v[136:139], v244 offset:34816
	ds_read_b128 v[140:143], v244 offset:35840
	s_mov_b32 m0, s92
	ds_read_b128 v[188:191], v244 offset:49152
	ds_read_b128 v[196:199], v244 offset:50176
	ds_read_b128 v[200:203], v244 offset:51200
	ds_read_b128 v[218:221], v244 offset:52224
	global_load_lds_dwordx4 v176, s[46:47]
	s_add_i32 m0, s92, 0x2000
	ds_read_b128 v[144:147], v216 offset:32768
	ds_read_b128 v[148:151], v216 offset:33792
	ds_read_b128 v[152:155], v216 offset:34816
	ds_read_b128 v[156:159], v216 offset:35840
	global_load_lds_dwordx4 v178, s[46:47]
	s_add_i32 m0, s92, 0x4000
	ds_read_b128 v[160:163], v216 offset:36864
	ds_read_b128 v[164:167], v216 offset:37888
	ds_read_b128 v[168:171], v216 offset:38912
	ds_read_b128 v[172:175], v216 offset:39936
	global_load_lds_dwordx4 v176, s[76:77]
	s_add_i32 m0, s92, 0x6000
	s_nop 0
	global_load_lds_dwordx4 v178, s[76:77]
	s_waitcnt lgkmcnt(0)
	s_barrier
	v_mfma_f32_16x16x32_bf16 v[124:127], v[128:131], v[144:147], v[124:127]
	v_mfma_f32_16x16x32_bf16 v[116:119], v[136:139], v[144:147], v[116:119]
	v_mfma_f32_16x16x32_bf16 v[108:111], v[128:131], v[152:155], v[108:111]
	v_mfma_f32_16x16x32_bf16 v[100:103], v[136:139], v[152:155], v[100:103]
	v_mfma_f32_16x16x32_bf16 v[92:95], v[128:131], v[160:163], v[92:95]
	v_mfma_f32_16x16x32_bf16 v[84:87], v[136:139], v[160:163], v[84:87]
	v_mfma_f32_16x16x32_bf16 v[76:79], v[128:131], v[168:171], v[76:79]
	v_mfma_f32_16x16x32_bf16 v[68:71], v[136:139], v[168:171], v[68:71]
	v_mfma_f32_16x16x32_bf16 v[124:127], v[132:135], v[148:151], v[124:127]
	v_mfma_f32_16x16x32_bf16 v[116:119], v[140:143], v[148:151], v[116:119]
	v_mfma_f32_16x16x32_bf16 v[108:111], v[132:135], v[156:159], v[108:111]
	v_mfma_f32_16x16x32_bf16 v[100:103], v[140:143], v[156:159], v[100:103]
	v_mfma_f32_16x16x32_bf16 v[92:95], v[132:135], v[164:167], v[92:95]
	v_mfma_f32_16x16x32_bf16 v[84:87], v[140:143], v[164:167], v[84:87]
	v_mfma_f32_16x16x32_bf16 v[76:79], v[132:135], v[172:175], v[76:79]
	v_mfma_f32_16x16x32_bf16 v[68:71], v[140:143], v[172:175], v[68:71]
	v_mfma_f32_16x16x32_bf16 v[120:123], v[188:191], v[144:147], v[120:123]
	v_mfma_f32_16x16x32_bf16 v[112:115], v[200:203], v[144:147], v[112:115]
	v_mfma_f32_16x16x32_bf16 v[104:107], v[188:191], v[152:155], v[104:107]
	v_mfma_f32_16x16x32_bf16 v[96:99], v[200:203], v[152:155], v[96:99]
	v_mfma_f32_16x16x32_bf16 v[88:91], v[188:191], v[160:163], v[88:91]
	v_mfma_f32_16x16x32_bf16 v[80:83], v[200:203], v[160:163], v[80:83]
	v_mfma_f32_16x16x32_bf16 v[72:75], v[188:191], v[168:171], v[72:75]
	v_mfma_f32_16x16x32_bf16 v[64:67], v[200:203], v[168:171], v[64:67]
	v_mfma_f32_16x16x32_bf16 v[120:123], v[196:199], v[148:151], v[120:123]
	v_mfma_f32_16x16x32_bf16 v[112:115], v[218:221], v[148:151], v[112:115]
	v_mfma_f32_16x16x32_bf16 v[104:107], v[196:199], v[156:159], v[104:107]
	v_mfma_f32_16x16x32_bf16 v[96:99], v[218:221], v[156:159], v[96:99]
	v_mfma_f32_16x16x32_bf16 v[88:91], v[196:199], v[164:167], v[88:91]
	v_mfma_f32_16x16x32_bf16 v[80:83], v[218:221], v[164:167], v[80:83]
	v_mfma_f32_16x16x32_bf16 v[72:75], v[196:199], v[172:175], v[72:75]
	v_mfma_f32_16x16x32_bf16 v[64:67], v[218:221], v[172:175], v[64:67]
	s_barrier
	s_add_u32 s76, s44, 0x80
	s_addc_u32 s77, s45, 0
	ds_read_b128 v[144:147], v216 offset:49152
	ds_read_b128 v[148:151], v216 offset:50176
	ds_read_b128 v[152:155], v216 offset:51200
	ds_read_b128 v[156:159], v216 offset:52224
	s_add_i32 m0, s92, 0x18000
	ds_read_b128 v[160:163], v216 offset:53248
	ds_read_b128 v[164:167], v216 offset:54272
	ds_read_b128 v[168:171], v216 offset:55296
	ds_read_b128 v[172:175], v216 offset:56320
	global_load_lds_dwordx4 v192, s[76:77]
	s_add_i32 m0, s92, 0x1a000
	s_nop 0
	global_load_lds_dwordx4 v180, s[76:77]
	s_add_u32 s76, s44, 0x80080
	s_addc_u32 s77, s45, 0
	s_add_i32 m0, s92, 0x1c000
	s_nop 0
	global_load_lds_dwordx4 v192, s[76:77]
	s_add_i32 m0, s92, 0x1e000
	s_nop 0
	global_load_lds_dwordx4 v180, s[76:77]
	s_waitcnt vmcnt(4)
	s_waitcnt lgkmcnt(0)
	s_barrier
	v_mfma_f32_16x16x32_bf16 v[60:63], v[128:131], v[144:147], v[60:63]
	v_mfma_f32_16x16x32_bf16 v[52:55], v[136:139], v[144:147], v[52:55]
	v_mfma_f32_16x16x32_bf16 v[44:47], v[128:131], v[152:155], v[44:47]
	v_mfma_f32_16x16x32_bf16 v[36:39], v[136:139], v[152:155], v[36:39]
	v_mfma_f32_16x16x32_bf16 v[28:31], v[128:131], v[160:163], v[28:31]
	v_mfma_f32_16x16x32_bf16 v[20:23], v[136:139], v[160:163], v[20:23]
	v_mfma_f32_16x16x32_bf16 v[12:15], v[128:131], v[168:171], v[12:15]
	v_mfma_f32_16x16x32_bf16 v[4:7], v[136:139], v[168:171], v[4:7]
	v_mfma_f32_16x16x32_bf16 v[60:63], v[132:135], v[148:151], v[60:63]
	v_mfma_f32_16x16x32_bf16 v[52:55], v[140:143], v[148:151], v[52:55]
	v_mfma_f32_16x16x32_bf16 v[44:47], v[132:135], v[156:159], v[44:47]
	v_mfma_f32_16x16x32_bf16 v[36:39], v[140:143], v[156:159], v[36:39]
	v_mfma_f32_16x16x32_bf16 v[28:31], v[132:135], v[164:167], v[28:31]
	v_mfma_f32_16x16x32_bf16 v[20:23], v[140:143], v[164:167], v[20:23]
	v_mfma_f32_16x16x32_bf16 v[12:15], v[132:135], v[172:175], v[12:15]
	v_mfma_f32_16x16x32_bf16 v[4:7], v[140:143], v[172:175], v[4:7]
	v_mfma_f32_16x16x32_bf16 v[56:59], v[188:191], v[144:147], v[56:59]
	v_mfma_f32_16x16x32_bf16 v[48:51], v[200:203], v[144:147], v[48:51]
	v_mfma_f32_16x16x32_bf16 v[40:43], v[188:191], v[152:155], v[40:43]
	v_mfma_f32_16x16x32_bf16 v[32:35], v[200:203], v[152:155], v[32:35]
	v_mfma_f32_16x16x32_bf16 v[24:27], v[188:191], v[160:163], v[24:27]
	v_mfma_f32_16x16x32_bf16 v[16:19], v[200:203], v[160:163], v[16:19]
	v_mfma_f32_16x16x32_bf16 v[8:11], v[188:191], v[168:171], v[8:11]
	v_mfma_f32_16x16x32_bf16 v[0:3], v[200:203], v[168:171], v[0:3]
	v_mfma_f32_16x16x32_bf16 v[56:59], v[196:199], v[148:151], v[56:59]
	v_mfma_f32_16x16x32_bf16 v[48:51], v[218:221], v[148:151], v[48:51]
	v_mfma_f32_16x16x32_bf16 v[40:43], v[196:199], v[156:159], v[40:43]
	v_mfma_f32_16x16x32_bf16 v[32:35], v[218:221], v[156:159], v[32:35]
	v_mfma_f32_16x16x32_bf16 v[24:27], v[196:199], v[164:167], v[24:27]
	v_mfma_f32_16x16x32_bf16 v[16:19], v[218:221], v[164:167], v[16:19]
	v_mfma_f32_16x16x32_bf16 v[8:11], v[196:199], v[172:175], v[8:11]
	v_mfma_f32_16x16x32_bf16 v[0:3], v[218:221], v[172:175], v[0:3]
	s_add_i32 s69, s69, 2
	s_add_u32 s40, s40, 0x100
	s_addc_u32 s41, s41, 0
	s_add_u32 s9, s9, 0x100
	s_addc_u32 s15, s15, 0
	s_cmp_gt_u32 s69, 29
	s_barrier
	s_cbranch_scc0 .LBB0_101
	v_mov_b32_e32 v232, 0xbfb8aa3b
	v_mov_b32_e32 v234, 1.0
	s_cmp_lt_i32 s75, 8
	s_mov_b32 s9, 1
	s_cbranch_scc1 .LBB0_110
	s_sub_i32 s4, s75, 30
	s_cmp_lt_u32 s4, 4
	s_mov_b32 s9, 2
	s_cbranch_scc1 .LBB0_110
	s_and_b32 s9, s75, 0x7ffffffc
	s_cmp_lt_i32 s9, 20
	s_cbranch_scc1 .LBB0_106
	s_cmp_lg_u32 s9, 20
	s_cselect_b64 s[4:5], -1, 0
	s_cbranch_execz .LBB0_107
	s_branch .LBB0_108

; __device__ __forceinline__ float silu_f(float v) { return v * __builtin_amdgcn_rcpf(1.f + __expf(-v)); }
;     __device__ __forceinline__ void epi(f32x4 (&acc)[2][2][4][2], const pg8::Unit& u, int wr, int wc, int fr, int fq) const {
;     ...
;                 const int row = row0 + ai * 128 + m * 16;
;                 const float rs = rsv[ai][m];
;                 f32x4 v[2][2];
; #pragma unroll
;                 for (int bj = 0; bj < 2; ++bj)
; #pragma unroll
;                     for (int n = 0; n < 2; ++n) v[bj][n] = acc[ai][bj][m][n] * rs;
;                 if (mode == 2) {
; #pragma unroll
;                     for (int bj = 0; bj < 2; ++bj)
; #pragma unroll
;                         for (int n = 0; n < 2; ++n)
; #pragma unroll
;                             for (int j = 0; j < 4; ++j) v[bj][n][j] = silu_f(v[bj][n][j]);
;                 } else if (mode == 3) {
;                     const float rsn = rs * -1.4426950408889634f;
; #pragma unroll
;                     for (int bj = 0; bj < 2; ++bj)
; #pragma unroll
;                         for (int n = 0; n < 2; ++n)
; #pragma unroll
;                             for (int j = 0; j < 4; ++j) v[bj][n][j] = __builtin_amdgcn_rcpf(1.0f + __builtin_amdgcn_exp2f(acc[ai][bj][m][n][j] * rsn));
;                 }
.LBB0_114:
	v_lshl_or_b32 v132, s75, 8, v206
	s_cmp_eq_u32 s9, 1
	v_ashrrev_i32_e32 v133, 31, v132
	s_mov_b64 s[4:5], -1
	s_cbranch_scc1 .LBB0_156
	s_cmp_gt_i32 s9, 2
	s_cbranch_scc0 .LBB0_117
	s_waitcnt lgkmcnt(0)
	v_mul_f32_e32 v146, 0xbfb8aa3b, v200
	v_mul_f32_e32 v147, v112, v146
	v_exp_f32_e32 v147, v147
	v_mul_f32_e32 v148, v113, v146
	v_exp_f32_e32 v149, v148
	v_pk_mul_f32 v[128:129], v[124:125], v[146:147] op_sel_hi:[1,0]
	v_add_f32_e32 v147, 1.0, v147
	v_pk_mul_f32 v[130:131], v[126:127], v[146:147] op_sel_hi:[1,0]
	v_pk_mul_f32 v[136:137], v[116:117], v[146:147] op_sel_hi:[1,0]
	v_pk_mul_f32 v[138:139], v[118:119], v[146:147] op_sel_hi:[1,0]
	v_pk_mul_f32 v[140:141], v[120:121], v[146:147] op_sel_hi:[1,0]
	v_pk_mul_f32 v[142:143], v[122:123], v[146:147] op_sel_hi:[1,0]
	v_rcp_f32_e32 v148, v147
	v_add_f32_e32 v147, 1.0, v149
	v_mul_f32_e32 v149, v114, v146
	v_mul_f32_e32 v146, v115, v146
	v_exp_f32_e32 v128, v128
	v_exp_f32_e32 v129, v129
	v_exp_f32_e32 v130, v130
	v_exp_f32_e32 v131, v131
	v_exp_f32_e32 v136, v136
	v_exp_f32_e32 v137, v137
	v_exp_f32_e32 v138, v138
	v_exp_f32_e32 v139, v139
	v_exp_f32_e32 v140, v140
	v_exp_f32_e32 v141, v141
	v_exp_f32_e32 v142, v142
	v_exp_f32_e32 v143, v143
	v_exp_f32_e32 v150, v149
	v_exp_f32_e32 v151, v146
	v_pk_add_f32 v[128:129], v[128:129], v[234:235] op_sel_hi:[1,0]
	v_pk_add_f32 v[130:131], v[130:131], v[234:235] op_sel_hi:[1,0]
	v_pk_add_f32 v[136:137], v[136:137], v[234:235] op_sel_hi:[1,0]
	v_pk_add_f32 v[138:139], v[138:139], v[234:235] op_sel_hi:[1,0]
	v_pk_add_f32 v[140:141], v[140:141], v[234:235] op_sel_hi:[1,0]
	v_pk_add_f32 v[142:143], v[142:143], v[234:235] op_sel_hi:[1,0]
	v_rcp_f32_e32 v149, v147
	v_add_f32_e32 v146, 1.0, v150
	v_add_f32_e32 v147, 1.0, v151
	v_rcp_f32_e32 v128, v128
	v_rcp_f32_e32 v129, v129
	v_rcp_f32_e32 v130, v130
	v_rcp_f32_e32 v131, v131
	v_rcp_f32_e32 v136, v136
	v_rcp_f32_e32 v137, v137
	v_rcp_f32_e32 v138, v138
	v_rcp_f32_e32 v139, v139
	v_rcp_f32_e32 v140, v140
	v_rcp_f32_e32 v141, v141
	v_rcp_f32_e32 v142, v142
	v_rcp_f32_e32 v143, v143
	v_rcp_f32_e32 v146, v146
	v_rcp_f32_e32 v147, v147
	s_mov_b64 s[4:5], 0
.LBB0_117:
	s_andn2_b64 vcc, exec, s[4:5]
	s_cbranch_vccnz .LBB0_120
	s_waitcnt lgkmcnt(0)
	v_pk_mul_f32 v[130:131], v[126:127], v[200:201] op_sel_hi:[1,0]
	v_pk_mul_f32 v[128:129], v[124:125], v[200:201] op_sel_hi:[1,0]
	v_pk_mul_f32 v[138:139], v[118:119], v[200:201] op_sel_hi:[1,0]
	v_pk_mul_f32 v[136:137], v[116:117], v[200:201] op_sel_hi:[1,0]
	v_pk_mul_f32 v[142:143], v[122:123], v[200:201] op_sel_hi:[1,0]
	v_pk_mul_f32 v[140:141], v[120:121], v[200:201] op_sel_hi:[1,0]
	v_pk_mul_f32 v[146:147], v[114:115], v[200:201] op_sel_hi:[1,0]
	s_cmp_eq_u32 s9, 2
	v_pk_mul_f32 v[148:149], v[112:113], v[200:201] op_sel_hi:[1,0]
	s_cbranch_scc0 .LBB0_120
	v_pk_mul_f32 v[150:151], v[128:129], v[232:233] op_sel_hi:[1,0]
	v_pk_mul_f32 v[152:153], v[130:131], v[232:233] op_sel_hi:[1,0]
	v_exp_f32_e32 v150, v150
	v_exp_f32_e32 v151, v151
	v_exp_f32_e32 v152, v152
	v_exp_f32_e32 v153, v153
	v_pk_add_f32 v[150:151], v[150:151], v[234:235] op_sel_hi:[1,0]
	v_pk_add_f32 v[152:153], v[152:153], v[234:235] op_sel_hi:[1,0]
	v_rcp_f32_e32 v150, v150
	v_rcp_f32_e32 v151, v151
	v_rcp_f32_e32 v152, v152
	v_rcp_f32_e32 v153, v153
	v_pk_mul_f32 v[128:129], v[128:129], v[150:151]
	v_pk_mul_f32 v[150:151], v[136:137], v[232:233] op_sel_hi:[1,0]
	v_pk_mul_f32 v[130:131], v[130:131], v[152:153]
	v_pk_mul_f32 v[152:153], v[138:139], v[232:233] op_sel_hi:[1,0]
	v_exp_f32_e32 v150, v150
	v_exp_f32_e32 v151, v151
	v_exp_f32_e32 v152, v152
	v_exp_f32_e32 v153, v153
	v_pk_add_f32 v[150:151], v[150:151], v[234:235] op_sel_hi:[1,0]
	v_pk_add_f32 v[152:153], v[152:153], v[234:235] op_sel_hi:[1,0]
	v_rcp_f32_e32 v150, v150
	v_rcp_f32_e32 v151, v151
	v_rcp_f32_e32 v152, v152
	v_rcp_f32_e32 v153, v153
	v_pk_mul_f32 v[136:137], v[136:137], v[150:151]
	v_pk_mul_f32 v[150:151], v[140:141], v[232:233] op_sel_hi:[1,0]
	v_pk_mul_f32 v[138:139], v[138:139], v[152:153]
	v_pk_mul_f32 v[152:153], v[142:143], v[232:233] op_sel_hi:[1,0]
	v_exp_f32_e32 v150, v150
	v_exp_f32_e32 v151, v151
	v_exp_f32_e32 v152, v152
	v_exp_f32_e32 v153, v153
	v_pk_add_f32 v[150:151], v[150:151], v[234:235] op_sel_hi:[1,0]
	v_pk_add_f32 v[152:153], v[152:153], v[234:235] op_sel_hi:[1,0]
	v_rcp_f32_e32 v150, v150
	v_rcp_f32_e32 v151, v151
	v_rcp_f32_e32 v152, v152
	v_rcp_f32_e32 v153, v153
	v_pk_mul_f32 v[140:141], v[140:141], v[150:151]
	v_pk_mul_f32 v[150:151], v[148:149], v[232:233] op_sel_hi:[1,0]
	v_pk_mul_f32 v[142:143], v[142:143], v[152:153]
	v_pk_mul_f32 v[152:153], v[146:147], v[232:233] op_sel_hi:[1,0]
	v_exp_f32_e32 v150, v150
	v_exp_f32_e32 v151, v151
	v_exp_f32_e32 v152, v152
	v_exp_f32_e32 v153, v153
	v_pk_add_f32 v[150:151], v[150:151], v[234:235] op_sel_hi:[1,0]
	v_pk_add_f32 v[152:153], v[152:153], v[234:235] op_sel_hi:[1,0]
	v_rcp_f32_e32 v150, v150
	v_rcp_f32_e32 v151, v151
	v_rcp_f32_e32 v152, v152
	v_rcp_f32_e32 v153, v153
	v_pk_mul_f32 v[148:149], v[148:149], v[150:151]
	v_pk_mul_f32 v[146:147], v[146:147], v[152:153]
; __device__ __forceinline__ unsigned cvt_pk_bf16(float lo, float hi) { unsigned r; asm volatile("v_cvt_pk_bf16_f32 %0, %1, %2" : "=v"(r) : "v"(lo), "v"(hi)); return r; }
; __device__ __forceinline__ float silu_f(float v) { return v * __builtin_amdgcn_rcpf(1.f + __expf(-v)); }
;     __device__ __forceinline__ void epi(f32x4 (&acc)[2][2][4][2], const pg8::Unit& u, int wr, int wc, int fr, int fq) const {
;     ...
;                 const int row = row0 + ai * 128 + m * 16;
;                 const float rs = rsv[ai][m];
;                 f32x4 v[2][2];
; #pragma unroll
;                 for (int bj = 0; bj < 2; ++bj)
; #pragma unroll
;                     for (int n = 0; n < 2; ++n) v[bj][n] = acc[ai][bj][m][n] * rs;
;                 if (mode == 2) {
; #pragma unroll
;                     for (int bj = 0; bj < 2; ++bj)
; #pragma unroll
;                         for (int n = 0; n < 2; ++n)
; #pragma unroll
;                             for (int j = 0; j < 4; ++j) v[bj][n][j] = silu_f(v[bj][n][j]);
;                 } else if (mode == 3) {
;                     const float rsn = rs * -1.4426950408889634f;
; #pragma unroll
;                     for (int bj = 0; bj < 2; ++bj)
; #pragma unroll
;                         for (int n = 0; n < 2; ++n)
; #pragma unroll
;                             for (int j = 0; j < 4; ++j) v[bj][n][j] = __builtin_amdgcn_rcpf(1.0f + __builtin_amdgcn_exp2f(acc[ai][bj][m][n][j] * rsn));
;                 }
;                 bf16_t* rowp = Z + (size_t)row * NIN + col0;
; #pragma unroll
;                 for (int bj = 0; bj < 2; ++bj) {
;                     u32x4 w; w.x = cvt_pk_bf16(v[bj][0][0], v[bj][0][1]); w.y = cvt_pk_bf16(v[bj][0][2], v[bj][0][3]); w.z = cvt_pk_bf16(v[bj][1][0], v[bj][1][1]); w.w = cvt_pk_bf16(v[bj][1][2], v[bj][1][3]);
;                     *(u32x4*)(rowp + bj * 128) = w;
;                 }
.LBB0_120:
	v_mov_b64_e32 v[150:151], s[26:27]
	v_mad_i64_i32 v[150:151], s[4:5], v188, s58, v[150:151]
	v_lshl_add_u64 v[150:151], v[132:133], 1, v[150:151]
	v_cvt_pk_bf16_f32 v128, v128, v129
	v_cvt_pk_bf16_f32 v129, v130, v131
	v_cvt_pk_bf16_f32 v130, v136, v137
	v_cvt_pk_bf16_f32 v131, v138, v139
	global_store_dwordx4 v[150:151], v[128:131], off
	s_cmp_gt_i32 s9, 2
	s_mov_b64 s[4:5], -1
	v_cvt_pk_bf16_f32 v128, v140, v141
	v_cvt_pk_bf16_f32 v129, v142, v143
	v_cvt_pk_bf16_f32 v130, v148, v149
	v_cvt_pk_bf16_f32 v131, v146, v147
	global_store_dwordx4 v[150:151], v[128:131], off offset:256
	s_cbranch_scc0 .LBB0_122
	s_waitcnt lgkmcnt(0)
	v_mul_f32_e32 v146, 0xbfb8aa3b, v201
	v_mul_f32_e32 v147, v96, v146
	v_exp_f32_e32 v147, v147
	v_mul_f32_e32 v148, v97, v146
	v_exp_f32_e32 v149, v148
	v_pk_mul_f32 v[128:129], v[108:109], v[146:147] op_sel_hi:[1,0]
	v_add_f32_e32 v147, 1.0, v147
	v_pk_mul_f32 v[130:131], v[110:111], v[146:147] op_sel_hi:[1,0]
	v_pk_mul_f32 v[136:137], v[100:101], v[146:147] op_sel_hi:[1,0]
	v_pk_mul_f32 v[138:139], v[102:103], v[146:147] op_sel_hi:[1,0]
	v_pk_mul_f32 v[140:141], v[104:105], v[146:147] op_sel_hi:[1,0]
	v_pk_mul_f32 v[142:143], v[106:107], v[146:147] op_sel_hi:[1,0]
	v_rcp_f32_e32 v148, v147
	v_add_f32_e32 v147, 1.0, v149
	v_mul_f32_e32 v149, v98, v146
	v_mul_f32_e32 v146, v99, v146
	v_exp_f32_e32 v128, v128
	v_exp_f32_e32 v129, v129
	v_exp_f32_e32 v130, v130
	v_exp_f32_e32 v131, v131
	v_exp_f32_e32 v136, v136
	v_exp_f32_e32 v137, v137
	v_exp_f32_e32 v138, v138
	v_exp_f32_e32 v139, v139
	v_exp_f32_e32 v140, v140
	v_exp_f32_e32 v141, v141
	v_exp_f32_e32 v142, v142
	v_exp_f32_e32 v143, v143
	v_exp_f32_e32 v150, v149
	v_exp_f32_e32 v151, v146
	v_pk_add_f32 v[128:129], v[128:129], v[234:235] op_sel_hi:[1,0]
	v_pk_add_f32 v[130:131], v[130:131], v[234:235] op_sel_hi:[1,0]
	v_pk_add_f32 v[136:137], v[136:137], v[234:235] op_sel_hi:[1,0]
	v_pk_add_f32 v[138:139], v[138:139], v[234:235] op_sel_hi:[1,0]
	v_pk_add_f32 v[140:141], v[140:141], v[234:235] op_sel_hi:[1,0]
	v_pk_add_f32 v[142:143], v[142:143], v[234:235] op_sel_hi:[1,0]
	v_rcp_f32_e32 v149, v147
	v_add_f32_e32 v146, 1.0, v150
	v_add_f32_e32 v147, 1.0, v151
	v_rcp_f32_e32 v128, v128
	v_rcp_f32_e32 v129, v129
	v_rcp_f32_e32 v130, v130
	v_rcp_f32_e32 v131, v131
	v_rcp_f32_e32 v136, v136
	v_rcp_f32_e32 v137, v137
	v_rcp_f32_e32 v138, v138
	v_rcp_f32_e32 v139, v139
	v_rcp_f32_e32 v140, v140
	v_rcp_f32_e32 v141, v141
	v_rcp_f32_e32 v142, v142
	v_rcp_f32_e32 v143, v143
	v_rcp_f32_e32 v146, v146
	v_rcp_f32_e32 v147, v147
	s_mov_b64 s[4:5], 0
.LBB0_122:
	s_andn2_b64 vcc, exec, s[4:5]
	s_cbranch_vccnz .LBB0_125
	s_waitcnt lgkmcnt(0)
	v_pk_mul_f32 v[130:131], v[110:111], v[200:201] op_sel:[0,1]
	v_pk_mul_f32 v[128:129], v[108:109], v[200:201] op_sel:[0,1]
	v_pk_mul_f32 v[138:139], v[102:103], v[200:201] op_sel:[0,1]
	v_pk_mul_f32 v[136:137], v[100:101], v[200:201] op_sel:[0,1]
	v_pk_mul_f32 v[142:143], v[106:107], v[200:201] op_sel:[0,1]
	v_pk_mul_f32 v[140:141], v[104:105], v[200:201] op_sel:[0,1]
	v_pk_mul_f32 v[146:147], v[98:99], v[200:201] op_sel:[0,1]
	s_cmp_eq_u32 s9, 2
	v_pk_mul_f32 v[148:149], v[96:97], v[200:201] op_sel:[0,1]
	s_cbranch_scc0 .LBB0_125
	v_pk_mul_f32 v[150:151], v[128:129], v[232:233] op_sel_hi:[1,0]
	v_pk_mul_f32 v[152:153], v[130:131], v[232:233] op_sel_hi:[1,0]
	v_exp_f32_e32 v150, v150
	v_exp_f32_e32 v151, v151
	v_exp_f32_e32 v152, v152
	v_exp_f32_e32 v153, v153
	v_pk_add_f32 v[150:151], v[150:151], v[234:235] op_sel_hi:[1,0]
	v_pk_add_f32 v[152:153], v[152:153], v[234:235] op_sel_hi:[1,0]
	v_rcp_f32_e32 v150, v150
	v_rcp_f32_e32 v151, v151
	v_rcp_f32_e32 v152, v152
	v_rcp_f32_e32 v153, v153
	v_pk_mul_f32 v[128:129], v[128:129], v[150:151]
	v_pk_mul_f32 v[150:151], v[136:137], v[232:233] op_sel_hi:[1,0]
	v_pk_mul_f32 v[130:131], v[130:131], v[152:153]
	v_pk_mul_f32 v[152:153], v[138:139], v[232:233] op_sel_hi:[1,0]
	v_exp_f32_e32 v150, v150
	v_exp_f32_e32 v151, v151
	v_exp_f32_e32 v152, v152
	v_exp_f32_e32 v153, v153
	v_pk_add_f32 v[150:151], v[150:151], v[234:235] op_sel_hi:[1,0]
	v_pk_add_f32 v[152:153], v[152:153], v[234:235] op_sel_hi:[1,0]
	v_rcp_f32_e32 v150, v150
	v_rcp_f32_e32 v151, v151
	v_rcp_f32_e32 v152, v152
	v_rcp_f32_e32 v153, v153
	v_pk_mul_f32 v[136:137], v[136:137], v[150:151]
	v_pk_mul_f32 v[150:151], v[140:141], v[232:233] op_sel_hi:[1,0]
	v_pk_mul_f32 v[138:139], v[138:139], v[152:153]
	v_pk_mul_f32 v[152:153], v[142:143], v[232:233] op_sel_hi:[1,0]
	v_exp_f32_e32 v150, v150
	v_exp_f32_e32 v151, v151
	v_exp_f32_e32 v152, v152
	v_exp_f32_e32 v153, v153
	v_pk_add_f32 v[150:151], v[150:151], v[234:235] op_sel_hi:[1,0]
	v_pk_add_f32 v[152:153], v[152:153], v[234:235] op_sel_hi:[1,0]
	v_rcp_f32_e32 v150, v150
	v_rcp_f32_e32 v151, v151
	v_rcp_f32_e32 v152, v152
	v_rcp_f32_e32 v153, v153
	v_pk_mul_f32 v[140:141], v[140:141], v[150:151]
	v_pk_mul_f32 v[150:151], v[148:149], v[232:233] op_sel_hi:[1,0]
	v_pk_mul_f32 v[142:143], v[142:143], v[152:153]
	v_pk_mul_f32 v[152:153], v[146:147], v[232:233] op_sel_hi:[1,0]
	v_exp_f32_e32 v150, v150
	v_exp_f32_e32 v151, v151
	v_exp_f32_e32 v152, v152
	v_exp_f32_e32 v153, v153
	v_pk_add_f32 v[150:151], v[150:151], v[234:235] op_sel_hi:[1,0]
	v_pk_add_f32 v[152:153], v[152:153], v[234:235] op_sel_hi:[1,0]
	v_rcp_f32_e32 v150, v150
	v_rcp_f32_e32 v151, v151
	v_rcp_f32_e32 v152, v152
	v_rcp_f32_e32 v153, v153
	v_pk_mul_f32 v[148:149], v[148:149], v[150:151]
	v_pk_mul_f32 v[146:147], v[146:147], v[152:153]
; __device__ __forceinline__ unsigned cvt_pk_bf16(float lo, float hi) { unsigned r; asm volatile("v_cvt_pk_bf16_f32 %0, %1, %2" : "=v"(r) : "v"(lo), "v"(hi)); return r; }
; __device__ __forceinline__ float silu_f(float v) { return v * __builtin_amdgcn_rcpf(1.f + __expf(-v)); }
;     __device__ __forceinline__ void epi(f32x4 (&acc)[2][2][4][2], const pg8::Unit& u, int wr, int wc, int fr, int fq) const {
;     ...
;                 const int row = row0 + ai * 128 + m * 16;
;                 const float rs = rsv[ai][m];
;                 f32x4 v[2][2];
; #pragma unroll
;                 for (int bj = 0; bj < 2; ++bj)
; #pragma unroll
;                     for (int n = 0; n < 2; ++n) v[bj][n] = acc[ai][bj][m][n] * rs;
;                 if (mode == 2) {
; #pragma unroll
;                     for (int bj = 0; bj < 2; ++bj)
; #pragma unroll
;                         for (int n = 0; n < 2; ++n)
; #pragma unroll
;                             for (int j = 0; j < 4; ++j) v[bj][n][j] = silu_f(v[bj][n][j]);
;                 } else if (mode == 3) {
;                     const float rsn = rs * -1.4426950408889634f;
; #pragma unroll
;                     for (int bj = 0; bj < 2; ++bj)
; #pragma unroll
;                         for (int n = 0; n < 2; ++n)
; #pragma unroll
;                             for (int j = 0; j < 4; ++j) v[bj][n][j] = __builtin_amdgcn_rcpf(1.0f + __builtin_amdgcn_exp2f(acc[ai][bj][m][n][j] * rsn));
;                 }
;                 bf16_t* rowp = Z + (size_t)row * NIN + col0;
; #pragma unroll
;                 for (int bj = 0; bj < 2; ++bj) {
;                     u32x4 w; w.x = cvt_pk_bf16(v[bj][0][0], v[bj][0][1]); w.y = cvt_pk_bf16(v[bj][0][2], v[bj][0][3]); w.z = cvt_pk_bf16(v[bj][1][0], v[bj][1][1]); w.w = cvt_pk_bf16(v[bj][1][2], v[bj][1][3]);
;                     *(u32x4*)(rowp + bj * 128) = w;
;                 }
.LBB0_125:
	v_mov_b64_e32 v[150:151], s[26:27]
	v_mad_i64_i32 v[150:151], s[4:5], v198, s58, v[150:151]
	v_lshl_add_u64 v[150:151], v[132:133], 1, v[150:151]
	v_cvt_pk_bf16_f32 v128, v128, v129
	v_cvt_pk_bf16_f32 v129, v130, v131
	v_cvt_pk_bf16_f32 v130, v136, v137
	v_cvt_pk_bf16_f32 v131, v138, v139
	global_store_dwordx4 v[150:151], v[128:131], off
	s_cmp_gt_i32 s9, 2
	s_mov_b64 s[4:5], -1
	v_cvt_pk_bf16_f32 v128, v140, v141
	v_cvt_pk_bf16_f32 v129, v142, v143
	v_cvt_pk_bf16_f32 v130, v148, v149
	v_cvt_pk_bf16_f32 v131, v146, v147
	global_store_dwordx4 v[150:151], v[128:131], off offset:256
	s_cbranch_scc0 .LBB0_127
	s_waitcnt lgkmcnt(0)
	v_mul_f32_e32 v146, 0xbfb8aa3b, v160
	v_mul_f32_e32 v147, v80, v146
	v_exp_f32_e32 v147, v147
	v_mul_f32_e32 v148, v81, v146
	v_exp_f32_e32 v149, v148
	v_pk_mul_f32 v[128:129], v[92:93], v[146:147] op_sel_hi:[1,0]
	v_add_f32_e32 v147, 1.0, v147
	v_pk_mul_f32 v[130:131], v[94:95], v[146:147] op_sel_hi:[1,0]
	v_pk_mul_f32 v[136:137], v[84:85], v[146:147] op_sel_hi:[1,0]
	v_pk_mul_f32 v[138:139], v[86:87], v[146:147] op_sel_hi:[1,0]
	v_pk_mul_f32 v[140:141], v[88:89], v[146:147] op_sel_hi:[1,0]
	v_pk_mul_f32 v[142:143], v[90:91], v[146:147] op_sel_hi:[1,0]
	v_rcp_f32_e32 v148, v147
	v_add_f32_e32 v147, 1.0, v149
	v_mul_f32_e32 v149, v82, v146
	v_mul_f32_e32 v146, v83, v146
	v_exp_f32_e32 v128, v128
	v_exp_f32_e32 v129, v129
	v_exp_f32_e32 v130, v130
	v_exp_f32_e32 v131, v131
	v_exp_f32_e32 v136, v136
	v_exp_f32_e32 v137, v137
	v_exp_f32_e32 v138, v138
	v_exp_f32_e32 v139, v139
	v_exp_f32_e32 v140, v140
	v_exp_f32_e32 v141, v141
	v_exp_f32_e32 v142, v142
	v_exp_f32_e32 v143, v143
	v_exp_f32_e32 v150, v149
	v_exp_f32_e32 v151, v146
	v_pk_add_f32 v[128:129], v[128:129], v[234:235] op_sel_hi:[1,0]
	v_pk_add_f32 v[130:131], v[130:131], v[234:235] op_sel_hi:[1,0]
	v_pk_add_f32 v[136:137], v[136:137], v[234:235] op_sel_hi:[1,0]
	v_pk_add_f32 v[138:139], v[138:139], v[234:235] op_sel_hi:[1,0]
	v_pk_add_f32 v[140:141], v[140:141], v[234:235] op_sel_hi:[1,0]
	v_pk_add_f32 v[142:143], v[142:143], v[234:235] op_sel_hi:[1,0]
	v_rcp_f32_e32 v149, v147
	v_add_f32_e32 v146, 1.0, v150
	v_add_f32_e32 v147, 1.0, v151
	v_rcp_f32_e32 v128, v128
	v_rcp_f32_e32 v129, v129
	v_rcp_f32_e32 v130, v130
	v_rcp_f32_e32 v131, v131
	v_rcp_f32_e32 v136, v136
	v_rcp_f32_e32 v137, v137
	v_rcp_f32_e32 v138, v138
	v_rcp_f32_e32 v139, v139
	v_rcp_f32_e32 v140, v140
	v_rcp_f32_e32 v141, v141
	v_rcp_f32_e32 v142, v142
	v_rcp_f32_e32 v143, v143
	v_rcp_f32_e32 v146, v146
	v_rcp_f32_e32 v147, v147
	s_mov_b64 s[4:5], 0
.LBB0_127:
	s_andn2_b64 vcc, exec, s[4:5]
	s_cbranch_vccnz .LBB0_130
	s_waitcnt lgkmcnt(0)
	v_pk_mul_f32 v[130:131], v[94:95], v[160:161] op_sel_hi:[1,0]
	v_pk_mul_f32 v[128:129], v[92:93], v[160:161] op_sel_hi:[1,0]
	v_pk_mul_f32 v[138:139], v[86:87], v[160:161] op_sel_hi:[1,0]
	v_pk_mul_f32 v[136:137], v[84:85], v[160:161] op_sel_hi:[1,0]
	v_pk_mul_f32 v[142:143], v[90:91], v[160:161] op_sel_hi:[1,0]
	v_pk_mul_f32 v[140:141], v[88:89], v[160:161] op_sel_hi:[1,0]
	v_pk_mul_f32 v[146:147], v[82:83], v[160:161] op_sel_hi:[1,0]
	s_cmp_eq_u32 s9, 2
	v_pk_mul_f32 v[148:149], v[80:81], v[160:161] op_sel_hi:[1,0]
	s_cbranch_scc0 .LBB0_130
	v_pk_mul_f32 v[150:151], v[128:129], v[232:233] op_sel_hi:[1,0]
	v_pk_mul_f32 v[152:153], v[130:131], v[232:233] op_sel_hi:[1,0]
	v_exp_f32_e32 v150, v150
	v_exp_f32_e32 v151, v151
	v_exp_f32_e32 v152, v152
	v_exp_f32_e32 v153, v153
	v_pk_add_f32 v[150:151], v[150:151], v[234:235] op_sel_hi:[1,0]
	v_pk_add_f32 v[152:153], v[152:153], v[234:235] op_sel_hi:[1,0]
	v_rcp_f32_e32 v150, v150
	v_rcp_f32_e32 v151, v151
	v_rcp_f32_e32 v152, v152
	v_rcp_f32_e32 v153, v153
	v_pk_mul_f32 v[128:129], v[128:129], v[150:151]
	v_pk_mul_f32 v[150:151], v[136:137], v[232:233] op_sel_hi:[1,0]
	v_pk_mul_f32 v[130:131], v[130:131], v[152:153]
	v_pk_mul_f32 v[152:153], v[138:139], v[232:233] op_sel_hi:[1,0]
	v_exp_f32_e32 v150, v150
	v_exp_f32_e32 v151, v151
	v_exp_f32_e32 v152, v152
	v_exp_f32_e32 v153, v153
	v_pk_add_f32 v[150:151], v[150:151], v[234:235] op_sel_hi:[1,0]
	v_pk_add_f32 v[152:153], v[152:153], v[234:235] op_sel_hi:[1,0]
	v_rcp_f32_e32 v150, v150
	v_rcp_f32_e32 v151, v151
	v_rcp_f32_e32 v152, v152
	v_rcp_f32_e32 v153, v153
	v_pk_mul_f32 v[136:137], v[136:137], v[150:151]
	v_pk_mul_f32 v[150:151], v[140:141], v[232:233] op_sel_hi:[1,0]
	v_pk_mul_f32 v[138:139], v[138:139], v[152:153]
	v_pk_mul_f32 v[152:153], v[142:143], v[232:233] op_sel_hi:[1,0]
	v_exp_f32_e32 v150, v150
	v_exp_f32_e32 v151, v151
	v_exp_f32_e32 v152, v152
	v_exp_f32_e32 v153, v153
	v_pk_add_f32 v[150:151], v[150:151], v[234:235] op_sel_hi:[1,0]
	v_pk_add_f32 v[152:153], v[152:153], v[234:235] op_sel_hi:[1,0]
	v_rcp_f32_e32 v150, v150
	v_rcp_f32_e32 v151, v151
	v_rcp_f32_e32 v152, v152
	v_rcp_f32_e32 v153, v153
	v_pk_mul_f32 v[140:141], v[140:141], v[150:151]
	v_pk_mul_f32 v[150:151], v[148:149], v[232:233] op_sel_hi:[1,0]
	v_pk_mul_f32 v[142:143], v[142:143], v[152:153]
	v_pk_mul_f32 v[152:153], v[146:147], v[232:233] op_sel_hi:[1,0]
	v_exp_f32_e32 v150, v150
	v_exp_f32_e32 v151, v151
	v_exp_f32_e32 v152, v152
	v_exp_f32_e32 v153, v153
	v_pk_add_f32 v[150:151], v[150:151], v[234:235] op_sel_hi:[1,0]
	v_pk_add_f32 v[152:153], v[152:153], v[234:235] op_sel_hi:[1,0]
	v_rcp_f32_e32 v150, v150
	v_rcp_f32_e32 v151, v151
	v_rcp_f32_e32 v152, v152
	v_rcp_f32_e32 v153, v153
	v_pk_mul_f32 v[148:149], v[148:149], v[150:151]
	v_pk_mul_f32 v[146:147], v[146:147], v[152:153]
; __device__ __forceinline__ unsigned cvt_pk_bf16(float lo, float hi) { unsigned r; asm volatile("v_cvt_pk_bf16_f32 %0, %1, %2" : "=v"(r) : "v"(lo), "v"(hi)); return r; }
; __device__ __forceinline__ float silu_f(float v) { return v * __builtin_amdgcn_rcpf(1.f + __expf(-v)); }
;     __device__ __forceinline__ void epi(f32x4 (&acc)[2][2][4][2], const pg8::Unit& u, int wr, int wc, int fr, int fq) const {
;     ...
;                 const int row = row0 + ai * 128 + m * 16;
;                 const float rs = rsv[ai][m];
;                 f32x4 v[2][2];
; #pragma unroll
;                 for (int bj = 0; bj < 2; ++bj)
; #pragma unroll
;                     for (int n = 0; n < 2; ++n) v[bj][n] = acc[ai][bj][m][n] * rs;
;                 if (mode == 2) {
; #pragma unroll
;                     for (int bj = 0; bj < 2; ++bj)
; #pragma unroll
;                         for (int n = 0; n < 2; ++n)
; #pragma unroll
;                             for (int j = 0; j < 4; ++j) v[bj][n][j] = silu_f(v[bj][n][j]);
;                 } else if (mode == 3) {
;                     const float rsn = rs * -1.4426950408889634f;
; #pragma unroll
;                     for (int bj = 0; bj < 2; ++bj)
; #pragma unroll
;                         for (int n = 0; n < 2; ++n)
; #pragma unroll
;                             for (int j = 0; j < 4; ++j) v[bj][n][j] = __builtin_amdgcn_rcpf(1.0f + __builtin_amdgcn_exp2f(acc[ai][bj][m][n][j] * rsn));
;                 }
;                 bf16_t* rowp = Z + (size_t)row * NIN + col0;
; #pragma unroll
;                 for (int bj = 0; bj < 2; ++bj) {
;                     u32x4 w; w.x = cvt_pk_bf16(v[bj][0][0], v[bj][0][1]); w.y = cvt_pk_bf16(v[bj][0][2], v[bj][0][3]); w.z = cvt_pk_bf16(v[bj][1][0], v[bj][1][1]); w.w = cvt_pk_bf16(v[bj][1][2], v[bj][1][3]);
;                     *(u32x4*)(rowp + bj * 128) = w;
;                 }
.LBB0_130:
	v_mov_b64_e32 v[150:151], s[26:27]
	v_mad_i64_i32 v[150:151], s[4:5], v196, s58, v[150:151]
	v_lshl_add_u64 v[150:151], v[132:133], 1, v[150:151]
	v_cvt_pk_bf16_f32 v128, v128, v129
	v_cvt_pk_bf16_f32 v129, v130, v131
	v_cvt_pk_bf16_f32 v130, v136, v137
	v_cvt_pk_bf16_f32 v131, v138, v139
	global_store_dwordx4 v[150:151], v[128:131], off
	s_cmp_gt_i32 s9, 2
	s_mov_b64 s[4:5], -1
	v_cvt_pk_bf16_f32 v128, v140, v141
	v_cvt_pk_bf16_f32 v129, v142, v143
	v_cvt_pk_bf16_f32 v130, v148, v149
	v_cvt_pk_bf16_f32 v131, v146, v147
	global_store_dwordx4 v[150:151], v[128:131], off offset:256
	s_cbranch_scc0 .LBB0_132
	s_waitcnt lgkmcnt(0)
	v_mul_f32_e32 v146, 0xbfb8aa3b, v161
	v_mul_f32_e32 v147, v64, v146
	v_exp_f32_e32 v147, v147
	v_mul_f32_e32 v148, v65, v146
	v_exp_f32_e32 v149, v148
	v_pk_mul_f32 v[128:129], v[76:77], v[146:147] op_sel_hi:[1,0]
	v_add_f32_e32 v147, 1.0, v147
	v_pk_mul_f32 v[130:131], v[78:79], v[146:147] op_sel_hi:[1,0]
	v_pk_mul_f32 v[136:137], v[68:69], v[146:147] op_sel_hi:[1,0]
	v_pk_mul_f32 v[138:139], v[70:71], v[146:147] op_sel_hi:[1,0]
	v_pk_mul_f32 v[140:141], v[72:73], v[146:147] op_sel_hi:[1,0]
	v_pk_mul_f32 v[142:143], v[74:75], v[146:147] op_sel_hi:[1,0]
	v_rcp_f32_e32 v148, v147
	v_add_f32_e32 v147, 1.0, v149
	v_mul_f32_e32 v149, v66, v146
	v_mul_f32_e32 v146, v67, v146
	v_exp_f32_e32 v128, v128
	v_exp_f32_e32 v129, v129
	v_exp_f32_e32 v130, v130
	v_exp_f32_e32 v131, v131
	v_exp_f32_e32 v136, v136
	v_exp_f32_e32 v137, v137
	v_exp_f32_e32 v138, v138
	v_exp_f32_e32 v139, v139
	v_exp_f32_e32 v140, v140
	v_exp_f32_e32 v141, v141
	v_exp_f32_e32 v142, v142
	v_exp_f32_e32 v143, v143
	v_exp_f32_e32 v150, v149
	v_exp_f32_e32 v151, v146
	v_pk_add_f32 v[128:129], v[128:129], v[234:235] op_sel_hi:[1,0]
	v_pk_add_f32 v[130:131], v[130:131], v[234:235] op_sel_hi:[1,0]
	v_pk_add_f32 v[136:137], v[136:137], v[234:235] op_sel_hi:[1,0]
	v_pk_add_f32 v[138:139], v[138:139], v[234:235] op_sel_hi:[1,0]
	v_pk_add_f32 v[140:141], v[140:141], v[234:235] op_sel_hi:[1,0]
	v_pk_add_f32 v[142:143], v[142:143], v[234:235] op_sel_hi:[1,0]
	v_rcp_f32_e32 v149, v147
	v_add_f32_e32 v146, 1.0, v150
	v_add_f32_e32 v147, 1.0, v151
	v_rcp_f32_e32 v128, v128
	v_rcp_f32_e32 v129, v129
	v_rcp_f32_e32 v130, v130
	v_rcp_f32_e32 v131, v131
	v_rcp_f32_e32 v136, v136
	v_rcp_f32_e32 v137, v137
	v_rcp_f32_e32 v138, v138
	v_rcp_f32_e32 v139, v139
	v_rcp_f32_e32 v140, v140
	v_rcp_f32_e32 v141, v141
	v_rcp_f32_e32 v142, v142
	v_rcp_f32_e32 v143, v143
	v_rcp_f32_e32 v146, v146
	v_rcp_f32_e32 v147, v147
	s_mov_b64 s[4:5], 0
.LBB0_132:
	s_andn2_b64 vcc, exec, s[4:5]
	s_cbranch_vccnz .LBB0_135
	s_waitcnt lgkmcnt(0)
	v_pk_mul_f32 v[130:131], v[78:79], v[160:161] op_sel:[0,1]
	v_pk_mul_f32 v[128:129], v[76:77], v[160:161] op_sel:[0,1]
	v_pk_mul_f32 v[138:139], v[70:71], v[160:161] op_sel:[0,1]
	v_pk_mul_f32 v[136:137], v[68:69], v[160:161] op_sel:[0,1]
	v_pk_mul_f32 v[142:143], v[74:75], v[160:161] op_sel:[0,1]
	v_pk_mul_f32 v[140:141], v[72:73], v[160:161] op_sel:[0,1]
	v_pk_mul_f32 v[146:147], v[66:67], v[160:161] op_sel:[0,1]
	s_cmp_eq_u32 s9, 2
	v_pk_mul_f32 v[148:149], v[64:65], v[160:161] op_sel:[0,1]
	s_cbranch_scc0 .LBB0_135
	v_pk_mul_f32 v[150:151], v[128:129], v[232:233] op_sel_hi:[1,0]
	v_pk_mul_f32 v[152:153], v[130:131], v[232:233] op_sel_hi:[1,0]
	v_exp_f32_e32 v150, v150
	v_exp_f32_e32 v151, v151
	v_exp_f32_e32 v152, v152
	v_exp_f32_e32 v153, v153
	v_pk_add_f32 v[150:151], v[150:151], v[234:235] op_sel_hi:[1,0]
	v_pk_add_f32 v[152:153], v[152:153], v[234:235] op_sel_hi:[1,0]
	v_rcp_f32_e32 v150, v150
	v_rcp_f32_e32 v151, v151
	v_rcp_f32_e32 v152, v152
	v_rcp_f32_e32 v153, v153
	v_pk_mul_f32 v[128:129], v[128:129], v[150:151]
	v_pk_mul_f32 v[150:151], v[136:137], v[232:233] op_sel_hi:[1,0]
	v_pk_mul_f32 v[130:131], v[130:131], v[152:153]
	v_pk_mul_f32 v[152:153], v[138:139], v[232:233] op_sel_hi:[1,0]
	v_exp_f32_e32 v150, v150
	v_exp_f32_e32 v151, v151
	v_exp_f32_e32 v152, v152
	v_exp_f32_e32 v153, v153
	v_pk_add_f32 v[150:151], v[150:151], v[234:235] op_sel_hi:[1,0]
	v_pk_add_f32 v[152:153], v[152:153], v[234:235] op_sel_hi:[1,0]
	v_rcp_f32_e32 v150, v150
	v_rcp_f32_e32 v151, v151
	v_rcp_f32_e32 v152, v152
	v_rcp_f32_e32 v153, v153
	v_pk_mul_f32 v[136:137], v[136:137], v[150:151]
	v_pk_mul_f32 v[150:151], v[140:141], v[232:233] op_sel_hi:[1,0]
	v_pk_mul_f32 v[138:139], v[138:139], v[152:153]
	v_pk_mul_f32 v[152:153], v[142:143], v[232:233] op_sel_hi:[1,0]
	v_exp_f32_e32 v150, v150
	v_exp_f32_e32 v151, v151
	v_exp_f32_e32 v152, v152
	v_exp_f32_e32 v153, v153
	v_pk_add_f32 v[150:151], v[150:151], v[234:235] op_sel_hi:[1,0]
	v_pk_add_f32 v[152:153], v[152:153], v[234:235] op_sel_hi:[1,0]
	v_rcp_f32_e32 v150, v150
	v_rcp_f32_e32 v151, v151
	v_rcp_f32_e32 v152, v152
	v_rcp_f32_e32 v153, v153
	v_pk_mul_f32 v[140:141], v[140:141], v[150:151]
	v_pk_mul_f32 v[150:151], v[148:149], v[232:233] op_sel_hi:[1,0]
	v_pk_mul_f32 v[142:143], v[142:143], v[152:153]
	v_pk_mul_f32 v[152:153], v[146:147], v[232:233] op_sel_hi:[1,0]
	v_exp_f32_e32 v150, v150
	v_exp_f32_e32 v151, v151
	v_exp_f32_e32 v152, v152
	v_exp_f32_e32 v153, v153
	v_pk_add_f32 v[150:151], v[150:151], v[234:235] op_sel_hi:[1,0]
	v_pk_add_f32 v[152:153], v[152:153], v[234:235] op_sel_hi:[1,0]
	v_rcp_f32_e32 v150, v150
	v_rcp_f32_e32 v151, v151
	v_rcp_f32_e32 v152, v152
	v_rcp_f32_e32 v153, v153
	v_pk_mul_f32 v[148:149], v[148:149], v[150:151]
	v_pk_mul_f32 v[146:147], v[146:147], v[152:153]
; __device__ __forceinline__ unsigned cvt_pk_bf16(float lo, float hi) { unsigned r; asm volatile("v_cvt_pk_bf16_f32 %0, %1, %2" : "=v"(r) : "v"(lo), "v"(hi)); return r; }
; __device__ __forceinline__ float silu_f(float v) { return v * __builtin_amdgcn_rcpf(1.f + __expf(-v)); }
;     __device__ __forceinline__ void epi(f32x4 (&acc)[2][2][4][2], const pg8::Unit& u, int wr, int wc, int fr, int fq) const {
;     ...
;                 const int row = row0 + ai * 128 + m * 16;
;                 const float rs = rsv[ai][m];
;                 f32x4 v[2][2];
; #pragma unroll
;                 for (int bj = 0; bj < 2; ++bj)
; #pragma unroll
;                     for (int n = 0; n < 2; ++n) v[bj][n] = acc[ai][bj][m][n] * rs;
;                 if (mode == 2) {
; #pragma unroll
;                     for (int bj = 0; bj < 2; ++bj)
; #pragma unroll
;                         for (int n = 0; n < 2; ++n)
; #pragma unroll
;                             for (int j = 0; j < 4; ++j) v[bj][n][j] = silu_f(v[bj][n][j]);
;                 } else if (mode == 3) {
;                     const float rsn = rs * -1.4426950408889634f;
; #pragma unroll
;                     for (int bj = 0; bj < 2; ++bj)
; #pragma unroll
;                         for (int n = 0; n < 2; ++n)
; #pragma unroll
;                             for (int j = 0; j < 4; ++j) v[bj][n][j] = __builtin_amdgcn_rcpf(1.0f + __builtin_amdgcn_exp2f(acc[ai][bj][m][n][j] * rsn));
;                 }
;                 bf16_t* rowp = Z + (size_t)row * NIN + col0;
; #pragma unroll
;                 for (int bj = 0; bj < 2; ++bj) {
;                     u32x4 w; w.x = cvt_pk_bf16(v[bj][0][0], v[bj][0][1]); w.y = cvt_pk_bf16(v[bj][0][2], v[bj][0][3]); w.z = cvt_pk_bf16(v[bj][1][0], v[bj][1][1]); w.w = cvt_pk_bf16(v[bj][1][2], v[bj][1][3]);
;                     *(u32x4*)(rowp + bj * 128) = w;
;                 }
.LBB0_135:
	v_mov_b64_e32 v[150:151], s[26:27]
	v_mad_i64_i32 v[150:151], s[4:5], v190, s58, v[150:151]
	v_lshl_add_u64 v[150:151], v[132:133], 1, v[150:151]
	v_cvt_pk_bf16_f32 v128, v128, v129
	v_cvt_pk_bf16_f32 v129, v130, v131
	v_cvt_pk_bf16_f32 v130, v136, v137
	v_cvt_pk_bf16_f32 v131, v138, v139
	global_store_dwordx4 v[150:151], v[128:131], off
	s_cmp_gt_i32 s9, 2
	s_mov_b64 s[4:5], -1
	v_cvt_pk_bf16_f32 v128, v140, v141
	v_cvt_pk_bf16_f32 v129, v142, v143
	v_cvt_pk_bf16_f32 v130, v148, v149
	v_cvt_pk_bf16_f32 v131, v146, v147
	global_store_dwordx4 v[150:151], v[128:131], off offset:256
	s_cbranch_scc0 .LBB0_137
	s_waitcnt lgkmcnt(0)
	v_mul_f32_e32 v146, 0xbfb8aa3b, v144
	v_mul_f32_e32 v147, v48, v146
	v_exp_f32_e32 v147, v147
	v_mul_f32_e32 v148, v49, v146
	v_exp_f32_e32 v149, v148
	v_pk_mul_f32 v[128:129], v[60:61], v[146:147] op_sel_hi:[1,0]
	v_add_f32_e32 v147, 1.0, v147
	v_pk_mul_f32 v[130:131], v[62:63], v[146:147] op_sel_hi:[1,0]
	v_pk_mul_f32 v[136:137], v[52:53], v[146:147] op_sel_hi:[1,0]
	v_pk_mul_f32 v[138:139], v[54:55], v[146:147] op_sel_hi:[1,0]
	v_pk_mul_f32 v[140:141], v[56:57], v[146:147] op_sel_hi:[1,0]
	v_pk_mul_f32 v[142:143], v[58:59], v[146:147] op_sel_hi:[1,0]
	v_rcp_f32_e32 v148, v147
	v_add_f32_e32 v147, 1.0, v149
	v_mul_f32_e32 v149, v50, v146
	v_mul_f32_e32 v146, v51, v146
	v_exp_f32_e32 v128, v128
	v_exp_f32_e32 v129, v129
	v_exp_f32_e32 v130, v130
	v_exp_f32_e32 v131, v131
	v_exp_f32_e32 v136, v136
	v_exp_f32_e32 v137, v137
	v_exp_f32_e32 v138, v138
	v_exp_f32_e32 v139, v139
	v_exp_f32_e32 v140, v140
	v_exp_f32_e32 v141, v141
	v_exp_f32_e32 v142, v142
	v_exp_f32_e32 v143, v143
	v_exp_f32_e32 v150, v149
	v_exp_f32_e32 v151, v146
	v_pk_add_f32 v[128:129], v[128:129], v[234:235] op_sel_hi:[1,0]
	v_pk_add_f32 v[130:131], v[130:131], v[234:235] op_sel_hi:[1,0]
	v_pk_add_f32 v[136:137], v[136:137], v[234:235] op_sel_hi:[1,0]
	v_pk_add_f32 v[138:139], v[138:139], v[234:235] op_sel_hi:[1,0]
	v_pk_add_f32 v[140:141], v[140:141], v[234:235] op_sel_hi:[1,0]
	v_pk_add_f32 v[142:143], v[142:143], v[234:235] op_sel_hi:[1,0]
	v_rcp_f32_e32 v149, v147
	v_add_f32_e32 v146, 1.0, v150
	v_add_f32_e32 v147, 1.0, v151
	v_rcp_f32_e32 v128, v128
	v_rcp_f32_e32 v129, v129
	v_rcp_f32_e32 v130, v130
	v_rcp_f32_e32 v131, v131
	v_rcp_f32_e32 v136, v136
	v_rcp_f32_e32 v137, v137
	v_rcp_f32_e32 v138, v138
	v_rcp_f32_e32 v139, v139
	v_rcp_f32_e32 v140, v140
	v_rcp_f32_e32 v141, v141
	v_rcp_f32_e32 v142, v142
	v_rcp_f32_e32 v143, v143
	v_rcp_f32_e32 v146, v146
	v_rcp_f32_e32 v147, v147
	s_mov_b64 s[4:5], 0
.LBB0_137:
	s_andn2_b64 vcc, exec, s[4:5]
	s_cbranch_vccnz .LBB0_140
	s_waitcnt lgkmcnt(0)
	v_pk_mul_f32 v[130:131], v[62:63], v[144:145] op_sel_hi:[1,0]
	v_pk_mul_f32 v[128:129], v[60:61], v[144:145] op_sel_hi:[1,0]
	v_pk_mul_f32 v[138:139], v[54:55], v[144:145] op_sel_hi:[1,0]
	v_pk_mul_f32 v[136:137], v[52:53], v[144:145] op_sel_hi:[1,0]
	v_pk_mul_f32 v[142:143], v[58:59], v[144:145] op_sel_hi:[1,0]
	v_pk_mul_f32 v[140:141], v[56:57], v[144:145] op_sel_hi:[1,0]
	v_pk_mul_f32 v[146:147], v[50:51], v[144:145] op_sel_hi:[1,0]
	s_cmp_eq_u32 s9, 2
	v_pk_mul_f32 v[148:149], v[48:49], v[144:145] op_sel_hi:[1,0]
	s_cbranch_scc0 .LBB0_140
	v_pk_mul_f32 v[150:151], v[128:129], v[232:233] op_sel_hi:[1,0]
	v_pk_mul_f32 v[152:153], v[130:131], v[232:233] op_sel_hi:[1,0]
	v_exp_f32_e32 v150, v150
	v_exp_f32_e32 v151, v151
	v_exp_f32_e32 v152, v152
	v_exp_f32_e32 v153, v153
	v_pk_add_f32 v[150:151], v[150:151], v[234:235] op_sel_hi:[1,0]
	v_pk_add_f32 v[152:153], v[152:153], v[234:235] op_sel_hi:[1,0]
	v_rcp_f32_e32 v150, v150
	v_rcp_f32_e32 v151, v151
	v_rcp_f32_e32 v152, v152
	v_rcp_f32_e32 v153, v153
	v_pk_mul_f32 v[128:129], v[128:129], v[150:151]
	v_pk_mul_f32 v[150:151], v[136:137], v[232:233] op_sel_hi:[1,0]
	v_pk_mul_f32 v[130:131], v[130:131], v[152:153]
	v_pk_mul_f32 v[152:153], v[138:139], v[232:233] op_sel_hi:[1,0]
	v_exp_f32_e32 v150, v150
	v_exp_f32_e32 v151, v151
	v_exp_f32_e32 v152, v152
	v_exp_f32_e32 v153, v153
	v_pk_add_f32 v[150:151], v[150:151], v[234:235] op_sel_hi:[1,0]
	v_pk_add_f32 v[152:153], v[152:153], v[234:235] op_sel_hi:[1,0]
	v_rcp_f32_e32 v150, v150
	v_rcp_f32_e32 v151, v151
	v_rcp_f32_e32 v152, v152
	v_rcp_f32_e32 v153, v153
	v_pk_mul_f32 v[136:137], v[136:137], v[150:151]
	v_pk_mul_f32 v[150:151], v[140:141], v[232:233] op_sel_hi:[1,0]
	v_pk_mul_f32 v[138:139], v[138:139], v[152:153]
	v_pk_mul_f32 v[152:153], v[142:143], v[232:233] op_sel_hi:[1,0]
	v_exp_f32_e32 v150, v150
	v_exp_f32_e32 v151, v151
	v_exp_f32_e32 v152, v152
	v_exp_f32_e32 v153, v153
	v_pk_add_f32 v[150:151], v[150:151], v[234:235] op_sel_hi:[1,0]
	v_pk_add_f32 v[152:153], v[152:153], v[234:235] op_sel_hi:[1,0]
	v_rcp_f32_e32 v150, v150
	v_rcp_f32_e32 v151, v151
	v_rcp_f32_e32 v152, v152
	v_rcp_f32_e32 v153, v153
	v_pk_mul_f32 v[140:141], v[140:141], v[150:151]
	v_pk_mul_f32 v[150:151], v[148:149], v[232:233] op_sel_hi:[1,0]
	v_pk_mul_f32 v[142:143], v[142:143], v[152:153]
	v_pk_mul_f32 v[152:153], v[146:147], v[232:233] op_sel_hi:[1,0]
	v_exp_f32_e32 v150, v150
	v_exp_f32_e32 v151, v151
	v_exp_f32_e32 v152, v152
	v_exp_f32_e32 v153, v153
	v_pk_add_f32 v[150:151], v[150:151], v[234:235] op_sel_hi:[1,0]
	v_pk_add_f32 v[152:153], v[152:153], v[234:235] op_sel_hi:[1,0]
	v_rcp_f32_e32 v150, v150
	v_rcp_f32_e32 v151, v151
	v_rcp_f32_e32 v152, v152
	v_rcp_f32_e32 v153, v153
	v_pk_mul_f32 v[148:149], v[148:149], v[150:151]
	v_pk_mul_f32 v[146:147], v[146:147], v[152:153]
; __device__ __forceinline__ unsigned cvt_pk_bf16(float lo, float hi) { unsigned r; asm volatile("v_cvt_pk_bf16_f32 %0, %1, %2" : "=v"(r) : "v"(lo), "v"(hi)); return r; }
; __device__ __forceinline__ float silu_f(float v) { return v * __builtin_amdgcn_rcpf(1.f + __expf(-v)); }
;     __device__ __forceinline__ void epi(f32x4 (&acc)[2][2][4][2], const pg8::Unit& u, int wr, int wc, int fr, int fq) const {
;     ...
;                 const int row = row0 + ai * 128 + m * 16;
;                 const float rs = rsv[ai][m];
;                 f32x4 v[2][2];
; #pragma unroll
;                 for (int bj = 0; bj < 2; ++bj)
; #pragma unroll
;                     for (int n = 0; n < 2; ++n) v[bj][n] = acc[ai][bj][m][n] * rs;
;                 if (mode == 2) {
; #pragma unroll
;                     for (int bj = 0; bj < 2; ++bj)
; #pragma unroll
;                         for (int n = 0; n < 2; ++n)
; #pragma unroll
;                             for (int j = 0; j < 4; ++j) v[bj][n][j] = silu_f(v[bj][n][j]);
;                 } else if (mode == 3) {
;                     const float rsn = rs * -1.4426950408889634f;
; #pragma unroll
;                     for (int bj = 0; bj < 2; ++bj)
; #pragma unroll
;                         for (int n = 0; n < 2; ++n)
; #pragma unroll
;                             for (int j = 0; j < 4; ++j) v[bj][n][j] = __builtin_amdgcn_rcpf(1.0f + __builtin_amdgcn_exp2f(acc[ai][bj][m][n][j] * rsn));
;                 }
;                 bf16_t* rowp = Z + (size_t)row * NIN + col0;
; #pragma unroll
;                 for (int bj = 0; bj < 2; ++bj) {
;                     u32x4 w; w.x = cvt_pk_bf16(v[bj][0][0], v[bj][0][1]); w.y = cvt_pk_bf16(v[bj][0][2], v[bj][0][3]); w.z = cvt_pk_bf16(v[bj][1][0], v[bj][1][1]); w.w = cvt_pk_bf16(v[bj][1][2], v[bj][1][3]);
;                     *(u32x4*)(rowp + bj * 128) = w;
;                 }
.LBB0_140:
	v_add_u32_e32 v152, 0x80, v188
	v_mov_b64_e32 v[150:151], s[26:27]
	v_mad_i64_i32 v[150:151], s[4:5], v152, s58, v[150:151]
	v_lshl_add_u64 v[150:151], v[132:133], 1, v[150:151]
	v_cvt_pk_bf16_f32 v128, v128, v129
	v_cvt_pk_bf16_f32 v129, v130, v131
	v_cvt_pk_bf16_f32 v130, v136, v137
	v_cvt_pk_bf16_f32 v131, v138, v139
	global_store_dwordx4 v[150:151], v[128:131], off
	s_cmp_gt_i32 s9, 2
	s_mov_b64 s[4:5], -1
	v_cvt_pk_bf16_f32 v128, v140, v141
	v_cvt_pk_bf16_f32 v129, v142, v143
	v_cvt_pk_bf16_f32 v130, v148, v149
	v_cvt_pk_bf16_f32 v131, v146, v147
	global_store_dwordx4 v[150:151], v[128:131], off offset:256
	s_cbranch_scc0 .LBB0_142
	s_waitcnt lgkmcnt(0)
	v_mul_f32_e32 v146, 0xbfb8aa3b, v145
	v_mul_f32_e32 v147, v32, v146
	v_exp_f32_e32 v147, v147
	v_mul_f32_e32 v148, v33, v146
	v_exp_f32_e32 v149, v148
	v_pk_mul_f32 v[128:129], v[44:45], v[146:147] op_sel_hi:[1,0]
	v_add_f32_e32 v147, 1.0, v147
	v_pk_mul_f32 v[130:131], v[46:47], v[146:147] op_sel_hi:[1,0]
	v_pk_mul_f32 v[136:137], v[36:37], v[146:147] op_sel_hi:[1,0]
	v_pk_mul_f32 v[138:139], v[38:39], v[146:147] op_sel_hi:[1,0]
	v_pk_mul_f32 v[140:141], v[40:41], v[146:147] op_sel_hi:[1,0]
	v_pk_mul_f32 v[142:143], v[42:43], v[146:147] op_sel_hi:[1,0]
	v_rcp_f32_e32 v148, v147
	v_add_f32_e32 v147, 1.0, v149
	v_mul_f32_e32 v149, v34, v146
	v_mul_f32_e32 v146, v35, v146
	v_exp_f32_e32 v128, v128
	v_exp_f32_e32 v129, v129
	v_exp_f32_e32 v130, v130
	v_exp_f32_e32 v131, v131
	v_exp_f32_e32 v136, v136
	v_exp_f32_e32 v137, v137
	v_exp_f32_e32 v138, v138
	v_exp_f32_e32 v139, v139
	v_exp_f32_e32 v140, v140
	v_exp_f32_e32 v141, v141
	v_exp_f32_e32 v142, v142
	v_exp_f32_e32 v143, v143
	v_exp_f32_e32 v150, v149
	v_exp_f32_e32 v151, v146
	v_pk_add_f32 v[128:129], v[128:129], v[234:235] op_sel_hi:[1,0]
	v_pk_add_f32 v[130:131], v[130:131], v[234:235] op_sel_hi:[1,0]
	v_pk_add_f32 v[136:137], v[136:137], v[234:235] op_sel_hi:[1,0]
	v_pk_add_f32 v[138:139], v[138:139], v[234:235] op_sel_hi:[1,0]
	v_pk_add_f32 v[140:141], v[140:141], v[234:235] op_sel_hi:[1,0]
	v_pk_add_f32 v[142:143], v[142:143], v[234:235] op_sel_hi:[1,0]
	v_rcp_f32_e32 v149, v147
	v_add_f32_e32 v146, 1.0, v150
	v_add_f32_e32 v147, 1.0, v151
	v_rcp_f32_e32 v128, v128
	v_rcp_f32_e32 v129, v129
	v_rcp_f32_e32 v130, v130
	v_rcp_f32_e32 v131, v131
	v_rcp_f32_e32 v136, v136
	v_rcp_f32_e32 v137, v137
	v_rcp_f32_e32 v138, v138
	v_rcp_f32_e32 v139, v139
	v_rcp_f32_e32 v140, v140
	v_rcp_f32_e32 v141, v141
	v_rcp_f32_e32 v142, v142
	v_rcp_f32_e32 v143, v143
	v_rcp_f32_e32 v146, v146
	v_rcp_f32_e32 v147, v147
	s_mov_b64 s[4:5], 0
.LBB0_142:
	s_andn2_b64 vcc, exec, s[4:5]
	s_cbranch_vccnz .LBB0_145
	s_waitcnt lgkmcnt(0)
	v_pk_mul_f32 v[130:131], v[46:47], v[144:145] op_sel:[0,1]
	v_pk_mul_f32 v[128:129], v[44:45], v[144:145] op_sel:[0,1]
	v_pk_mul_f32 v[138:139], v[38:39], v[144:145] op_sel:[0,1]
	v_pk_mul_f32 v[136:137], v[36:37], v[144:145] op_sel:[0,1]
	v_pk_mul_f32 v[142:143], v[42:43], v[144:145] op_sel:[0,1]
	v_pk_mul_f32 v[140:141], v[40:41], v[144:145] op_sel:[0,1]
	v_pk_mul_f32 v[146:147], v[34:35], v[144:145] op_sel:[0,1]
	s_cmp_eq_u32 s9, 2
	v_pk_mul_f32 v[148:149], v[32:33], v[144:145] op_sel:[0,1]
	s_cbranch_scc0 .LBB0_145
	v_pk_mul_f32 v[150:151], v[128:129], v[232:233] op_sel_hi:[1,0]
	v_pk_mul_f32 v[152:153], v[130:131], v[232:233] op_sel_hi:[1,0]
	v_exp_f32_e32 v150, v150
	v_exp_f32_e32 v151, v151
	v_exp_f32_e32 v152, v152
	v_exp_f32_e32 v153, v153
	v_pk_add_f32 v[150:151], v[150:151], v[234:235] op_sel_hi:[1,0]
	v_pk_add_f32 v[152:153], v[152:153], v[234:235] op_sel_hi:[1,0]
	v_rcp_f32_e32 v150, v150
	v_rcp_f32_e32 v151, v151
	v_rcp_f32_e32 v152, v152
	v_rcp_f32_e32 v153, v153
	v_pk_mul_f32 v[128:129], v[128:129], v[150:151]
	v_pk_mul_f32 v[150:151], v[136:137], v[232:233] op_sel_hi:[1,0]
	v_pk_mul_f32 v[130:131], v[130:131], v[152:153]
	v_pk_mul_f32 v[152:153], v[138:139], v[232:233] op_sel_hi:[1,0]
	v_exp_f32_e32 v150, v150
	v_exp_f32_e32 v151, v151
	v_exp_f32_e32 v152, v152
	v_exp_f32_e32 v153, v153
	v_pk_add_f32 v[150:151], v[150:151], v[234:235] op_sel_hi:[1,0]
	v_pk_add_f32 v[152:153], v[152:153], v[234:235] op_sel_hi:[1,0]
	v_rcp_f32_e32 v150, v150
	v_rcp_f32_e32 v151, v151
	v_rcp_f32_e32 v152, v152
	v_rcp_f32_e32 v153, v153
	v_pk_mul_f32 v[136:137], v[136:137], v[150:151]
	v_pk_mul_f32 v[150:151], v[140:141], v[232:233] op_sel_hi:[1,0]
	v_pk_mul_f32 v[138:139], v[138:139], v[152:153]
	v_pk_mul_f32 v[152:153], v[142:143], v[232:233] op_sel_hi:[1,0]
	v_exp_f32_e32 v150, v150
	v_exp_f32_e32 v151, v151
	v_exp_f32_e32 v152, v152
	v_exp_f32_e32 v153, v153
	v_pk_add_f32 v[150:151], v[150:151], v[234:235] op_sel_hi:[1,0]
	v_pk_add_f32 v[152:153], v[152:153], v[234:235] op_sel_hi:[1,0]
	v_rcp_f32_e32 v150, v150
	v_rcp_f32_e32 v151, v151
	v_rcp_f32_e32 v152, v152
	v_rcp_f32_e32 v153, v153
	v_pk_mul_f32 v[140:141], v[140:141], v[150:151]
	v_pk_mul_f32 v[150:151], v[148:149], v[232:233] op_sel_hi:[1,0]
	v_pk_mul_f32 v[142:143], v[142:143], v[152:153]
	v_pk_mul_f32 v[152:153], v[146:147], v[232:233] op_sel_hi:[1,0]
	v_exp_f32_e32 v150, v150
	v_exp_f32_e32 v151, v151
	v_exp_f32_e32 v152, v152
	v_exp_f32_e32 v153, v153
	v_pk_add_f32 v[150:151], v[150:151], v[234:235] op_sel_hi:[1,0]
	v_pk_add_f32 v[152:153], v[152:153], v[234:235] op_sel_hi:[1,0]
	v_rcp_f32_e32 v150, v150
	v_rcp_f32_e32 v151, v151
	v_rcp_f32_e32 v152, v152
	v_rcp_f32_e32 v153, v153
	v_pk_mul_f32 v[148:149], v[148:149], v[150:151]
	v_pk_mul_f32 v[146:147], v[146:147], v[152:153]
; __device__ __forceinline__ unsigned cvt_pk_bf16(float lo, float hi) { unsigned r; asm volatile("v_cvt_pk_bf16_f32 %0, %1, %2" : "=v"(r) : "v"(lo), "v"(hi)); return r; }
; __device__ __forceinline__ float silu_f(float v) { return v * __builtin_amdgcn_rcpf(1.f + __expf(-v)); }
;     __device__ __forceinline__ void epi(f32x4 (&acc)[2][2][4][2], const pg8::Unit& u, int wr, int wc, int fr, int fq) const {
;     ...
;                 const int row = row0 + ai * 128 + m * 16;
;                 const float rs = rsv[ai][m];
;                 f32x4 v[2][2];
; #pragma unroll
;                 for (int bj = 0; bj < 2; ++bj)
; #pragma unroll
;                     for (int n = 0; n < 2; ++n) v[bj][n] = acc[ai][bj][m][n] * rs;
;                 if (mode == 2) {
; #pragma unroll
;                     for (int bj = 0; bj < 2; ++bj)
; #pragma unroll
;                         for (int n = 0; n < 2; ++n)
; #pragma unroll
;                             for (int j = 0; j < 4; ++j) v[bj][n][j] = silu_f(v[bj][n][j]);
;                 } else if (mode == 3) {
;                     const float rsn = rs * -1.4426950408889634f;
; #pragma unroll
;                     for (int bj = 0; bj < 2; ++bj)
; #pragma unroll
;                         for (int n = 0; n < 2; ++n)
; #pragma unroll
;                             for (int j = 0; j < 4; ++j) v[bj][n][j] = __builtin_amdgcn_rcpf(1.0f + __builtin_amdgcn_exp2f(acc[ai][bj][m][n][j] * rsn));
;                 }
;                 bf16_t* rowp = Z + (size_t)row * NIN + col0;
; #pragma unroll
;                 for (int bj = 0; bj < 2; ++bj) {
;                     u32x4 w; w.x = cvt_pk_bf16(v[bj][0][0], v[bj][0][1]); w.y = cvt_pk_bf16(v[bj][0][2], v[bj][0][3]); w.z = cvt_pk_bf16(v[bj][1][0], v[bj][1][1]); w.w = cvt_pk_bf16(v[bj][1][2], v[bj][1][3]);
;                     *(u32x4*)(rowp + bj * 128) = w;
;                 }
.LBB0_145:
	v_add_u32_e32 v152, 0x90, v188
	v_mov_b64_e32 v[150:151], s[26:27]
	v_mad_i64_i32 v[150:151], s[4:5], v152, s58, v[150:151]
	v_lshl_add_u64 v[150:151], v[132:133], 1, v[150:151]
	v_cvt_pk_bf16_f32 v128, v128, v129
	v_cvt_pk_bf16_f32 v129, v130, v131
	v_cvt_pk_bf16_f32 v130, v136, v137
	v_cvt_pk_bf16_f32 v131, v138, v139
	global_store_dwordx4 v[150:151], v[128:131], off
	s_cmp_gt_i32 s9, 2
	s_mov_b64 s[4:5], -1
	v_cvt_pk_bf16_f32 v128, v140, v141
	v_cvt_pk_bf16_f32 v129, v142, v143
	v_cvt_pk_bf16_f32 v130, v148, v149
	v_cvt_pk_bf16_f32 v131, v146, v147
	global_store_dwordx4 v[150:151], v[128:131], off offset:256
	s_cbranch_scc0 .LBB0_147
	s_waitcnt lgkmcnt(0)
	v_mul_f32_e32 v146, 0xbfb8aa3b, v134
	v_mul_f32_e32 v147, v16, v146
	v_exp_f32_e32 v147, v147
	v_mul_f32_e32 v148, v17, v146
	v_exp_f32_e32 v149, v148
	v_pk_mul_f32 v[128:129], v[28:29], v[146:147] op_sel_hi:[1,0]
	v_add_f32_e32 v147, 1.0, v147
	v_pk_mul_f32 v[130:131], v[30:31], v[146:147] op_sel_hi:[1,0]
	v_pk_mul_f32 v[136:137], v[20:21], v[146:147] op_sel_hi:[1,0]
	v_pk_mul_f32 v[138:139], v[22:23], v[146:147] op_sel_hi:[1,0]
	v_pk_mul_f32 v[140:141], v[24:25], v[146:147] op_sel_hi:[1,0]
	v_pk_mul_f32 v[142:143], v[26:27], v[146:147] op_sel_hi:[1,0]
	v_rcp_f32_e32 v148, v147
	v_add_f32_e32 v147, 1.0, v149
	v_mul_f32_e32 v149, v18, v146
	v_mul_f32_e32 v146, v19, v146
	v_exp_f32_e32 v128, v128
	v_exp_f32_e32 v129, v129
	v_exp_f32_e32 v130, v130
	v_exp_f32_e32 v131, v131
	v_exp_f32_e32 v136, v136
	v_exp_f32_e32 v137, v137
	v_exp_f32_e32 v138, v138
	v_exp_f32_e32 v139, v139
	v_exp_f32_e32 v140, v140
	v_exp_f32_e32 v141, v141
	v_exp_f32_e32 v142, v142
	v_exp_f32_e32 v143, v143
	v_exp_f32_e32 v150, v149
	v_exp_f32_e32 v151, v146
	v_pk_add_f32 v[128:129], v[128:129], v[234:235] op_sel_hi:[1,0]
	v_pk_add_f32 v[130:131], v[130:131], v[234:235] op_sel_hi:[1,0]
	v_pk_add_f32 v[136:137], v[136:137], v[234:235] op_sel_hi:[1,0]
	v_pk_add_f32 v[138:139], v[138:139], v[234:235] op_sel_hi:[1,0]
	v_pk_add_f32 v[140:141], v[140:141], v[234:235] op_sel_hi:[1,0]
	v_pk_add_f32 v[142:143], v[142:143], v[234:235] op_sel_hi:[1,0]
	v_rcp_f32_e32 v149, v147
	v_add_f32_e32 v146, 1.0, v150
	v_add_f32_e32 v147, 1.0, v151
	v_rcp_f32_e32 v128, v128
	v_rcp_f32_e32 v129, v129
	v_rcp_f32_e32 v130, v130
	v_rcp_f32_e32 v131, v131
	v_rcp_f32_e32 v136, v136
	v_rcp_f32_e32 v137, v137
	v_rcp_f32_e32 v138, v138
	v_rcp_f32_e32 v139, v139
	v_rcp_f32_e32 v140, v140
	v_rcp_f32_e32 v141, v141
	v_rcp_f32_e32 v142, v142
	v_rcp_f32_e32 v143, v143
	v_rcp_f32_e32 v146, v146
	v_rcp_f32_e32 v147, v147
	s_mov_b64 s[4:5], 0
.LBB0_147:
	s_andn2_b64 vcc, exec, s[4:5]
	s_cbranch_vccnz .LBB0_150
	s_waitcnt lgkmcnt(0)
	v_pk_mul_f32 v[130:131], v[30:31], v[134:135] op_sel_hi:[1,0]
	v_pk_mul_f32 v[128:129], v[28:29], v[134:135] op_sel_hi:[1,0]
	v_pk_mul_f32 v[138:139], v[22:23], v[134:135] op_sel_hi:[1,0]
	v_pk_mul_f32 v[136:137], v[20:21], v[134:135] op_sel_hi:[1,0]
	v_pk_mul_f32 v[142:143], v[26:27], v[134:135] op_sel_hi:[1,0]
	v_pk_mul_f32 v[140:141], v[24:25], v[134:135] op_sel_hi:[1,0]
	v_pk_mul_f32 v[146:147], v[18:19], v[134:135] op_sel_hi:[1,0]
	s_cmp_eq_u32 s9, 2
	v_pk_mul_f32 v[148:149], v[16:17], v[134:135] op_sel_hi:[1,0]
	s_cbranch_scc0 .LBB0_150
	v_pk_mul_f32 v[150:151], v[128:129], v[232:233] op_sel_hi:[1,0]
	v_pk_mul_f32 v[152:153], v[130:131], v[232:233] op_sel_hi:[1,0]
	v_exp_f32_e32 v150, v150
	v_exp_f32_e32 v151, v151
	v_exp_f32_e32 v152, v152
	v_exp_f32_e32 v153, v153
	v_pk_add_f32 v[150:151], v[150:151], v[234:235] op_sel_hi:[1,0]
	v_pk_add_f32 v[152:153], v[152:153], v[234:235] op_sel_hi:[1,0]
	v_rcp_f32_e32 v150, v150
	v_rcp_f32_e32 v151, v151
	v_rcp_f32_e32 v152, v152
	v_rcp_f32_e32 v153, v153
	v_pk_mul_f32 v[128:129], v[128:129], v[150:151]
	v_pk_mul_f32 v[150:151], v[136:137], v[232:233] op_sel_hi:[1,0]
	v_pk_mul_f32 v[130:131], v[130:131], v[152:153]
	v_pk_mul_f32 v[152:153], v[138:139], v[232:233] op_sel_hi:[1,0]
	v_exp_f32_e32 v150, v150
	v_exp_f32_e32 v151, v151
	v_exp_f32_e32 v152, v152
	v_exp_f32_e32 v153, v153
	v_pk_add_f32 v[150:151], v[150:151], v[234:235] op_sel_hi:[1,0]
	v_pk_add_f32 v[152:153], v[152:153], v[234:235] op_sel_hi:[1,0]
	v_rcp_f32_e32 v150, v150
	v_rcp_f32_e32 v151, v151
	v_rcp_f32_e32 v152, v152
	v_rcp_f32_e32 v153, v153
	v_pk_mul_f32 v[136:137], v[136:137], v[150:151]
	v_pk_mul_f32 v[150:151], v[140:141], v[232:233] op_sel_hi:[1,0]
	v_pk_mul_f32 v[138:139], v[138:139], v[152:153]
	v_pk_mul_f32 v[152:153], v[142:143], v[232:233] op_sel_hi:[1,0]
	v_exp_f32_e32 v150, v150
	v_exp_f32_e32 v151, v151
	v_exp_f32_e32 v152, v152
	v_exp_f32_e32 v153, v153
	v_pk_add_f32 v[150:151], v[150:151], v[234:235] op_sel_hi:[1,0]
	v_pk_add_f32 v[152:153], v[152:153], v[234:235] op_sel_hi:[1,0]
	v_rcp_f32_e32 v150, v150
	v_rcp_f32_e32 v151, v151
	v_rcp_f32_e32 v152, v152
	v_rcp_f32_e32 v153, v153
	v_pk_mul_f32 v[140:141], v[140:141], v[150:151]
	v_pk_mul_f32 v[150:151], v[148:149], v[232:233] op_sel_hi:[1,0]
	v_pk_mul_f32 v[142:143], v[142:143], v[152:153]
	v_pk_mul_f32 v[152:153], v[146:147], v[232:233] op_sel_hi:[1,0]
	v_exp_f32_e32 v150, v150
	v_exp_f32_e32 v151, v151
	v_exp_f32_e32 v152, v152
	v_exp_f32_e32 v153, v153
	v_pk_add_f32 v[150:151], v[150:151], v[234:235] op_sel_hi:[1,0]
	v_pk_add_f32 v[152:153], v[152:153], v[234:235] op_sel_hi:[1,0]
	v_rcp_f32_e32 v150, v150
	v_rcp_f32_e32 v151, v151
	v_rcp_f32_e32 v152, v152
	v_rcp_f32_e32 v153, v153
	v_pk_mul_f32 v[148:149], v[148:149], v[150:151]
	v_pk_mul_f32 v[146:147], v[146:147], v[152:153]
; __device__ __forceinline__ unsigned cvt_pk_bf16(float lo, float hi) { unsigned r; asm volatile("v_cvt_pk_bf16_f32 %0, %1, %2" : "=v"(r) : "v"(lo), "v"(hi)); return r; }
; __device__ __forceinline__ float silu_f(float v) { return v * __builtin_amdgcn_rcpf(1.f + __expf(-v)); }
;     __device__ __forceinline__ void epi(f32x4 (&acc)[2][2][4][2], const pg8::Unit& u, int wr, int wc, int fr, int fq) const {
;     ...
;                 const int row = row0 + ai * 128 + m * 16;
;                 const float rs = rsv[ai][m];
;                 f32x4 v[2][2];
; #pragma unroll
;                 for (int bj = 0; bj < 2; ++bj)
; #pragma unroll
;                     for (int n = 0; n < 2; ++n) v[bj][n] = acc[ai][bj][m][n] * rs;
;                 if (mode == 2) {
; #pragma unroll
;                     for (int bj = 0; bj < 2; ++bj)
; #pragma unroll
;                         for (int n = 0; n < 2; ++n)
; #pragma unroll
;                             for (int j = 0; j < 4; ++j) v[bj][n][j] = silu_f(v[bj][n][j]);
;                 } else if (mode == 3) {
;                     const float rsn = rs * -1.4426950408889634f;
; #pragma unroll
;                     for (int bj = 0; bj < 2; ++bj)
; #pragma unroll
;                         for (int n = 0; n < 2; ++n)
; #pragma unroll
;                             for (int j = 0; j < 4; ++j) v[bj][n][j] = __builtin_amdgcn_rcpf(1.0f + __builtin_amdgcn_exp2f(acc[ai][bj][m][n][j] * rsn));
;                 }
;                 bf16_t* rowp = Z + (size_t)row * NIN + col0;
; #pragma unroll
;                 for (int bj = 0; bj < 2; ++bj) {
;                     u32x4 w; w.x = cvt_pk_bf16(v[bj][0][0], v[bj][0][1]); w.y = cvt_pk_bf16(v[bj][0][2], v[bj][0][3]); w.z = cvt_pk_bf16(v[bj][1][0], v[bj][1][1]); w.w = cvt_pk_bf16(v[bj][1][2], v[bj][1][3]);
;                     *(u32x4*)(rowp + bj * 128) = w;
;                 }
.LBB0_150:
	v_add_u32_e32 v152, 0xa0, v188
	v_mov_b64_e32 v[150:151], s[26:27]
	v_mad_i64_i32 v[150:151], s[4:5], v152, s58, v[150:151]
	v_lshl_add_u64 v[150:151], v[132:133], 1, v[150:151]
	v_cvt_pk_bf16_f32 v128, v128, v129
	v_cvt_pk_bf16_f32 v129, v130, v131
	v_cvt_pk_bf16_f32 v130, v136, v137
	v_cvt_pk_bf16_f32 v131, v138, v139
	global_store_dwordx4 v[150:151], v[128:131], off
	s_cmp_gt_i32 s9, 2
	s_mov_b64 s[4:5], -1
	v_cvt_pk_bf16_f32 v128, v140, v141
	v_cvt_pk_bf16_f32 v129, v142, v143
	v_cvt_pk_bf16_f32 v130, v148, v149
	v_cvt_pk_bf16_f32 v131, v146, v147
	global_store_dwordx4 v[150:151], v[128:131], off offset:256
	s_cbranch_scc0 .LBB0_152
	s_waitcnt lgkmcnt(0)
	v_mul_f32_e32 v146, 0xbfb8aa3b, v135
	v_mul_f32_e32 v147, v0, v146
	v_exp_f32_e32 v147, v147
	v_mul_f32_e32 v148, v1, v146
	v_exp_f32_e32 v149, v148
	v_pk_mul_f32 v[128:129], v[12:13], v[146:147] op_sel_hi:[1,0]
	v_add_f32_e32 v147, 1.0, v147
	v_pk_mul_f32 v[130:131], v[14:15], v[146:147] op_sel_hi:[1,0]
	v_pk_mul_f32 v[136:137], v[4:5], v[146:147] op_sel_hi:[1,0]
	v_pk_mul_f32 v[138:139], v[6:7], v[146:147] op_sel_hi:[1,0]
	v_pk_mul_f32 v[140:141], v[8:9], v[146:147] op_sel_hi:[1,0]
	v_pk_mul_f32 v[142:143], v[10:11], v[146:147] op_sel_hi:[1,0]
	v_rcp_f32_e32 v148, v147
	v_add_f32_e32 v147, 1.0, v149
	v_mul_f32_e32 v149, v2, v146
	v_mul_f32_e32 v146, v3, v146
	v_exp_f32_e32 v128, v128
	v_exp_f32_e32 v129, v129
	v_exp_f32_e32 v130, v130
	v_exp_f32_e32 v131, v131
	v_exp_f32_e32 v136, v136
	v_exp_f32_e32 v137, v137
	v_exp_f32_e32 v138, v138
	v_exp_f32_e32 v139, v139
	v_exp_f32_e32 v140, v140
	v_exp_f32_e32 v141, v141
	v_exp_f32_e32 v142, v142
	v_exp_f32_e32 v143, v143
	v_exp_f32_e32 v150, v149
	v_exp_f32_e32 v151, v146
	v_pk_add_f32 v[128:129], v[128:129], v[234:235] op_sel_hi:[1,0]
	v_pk_add_f32 v[130:131], v[130:131], v[234:235] op_sel_hi:[1,0]
	v_pk_add_f32 v[136:137], v[136:137], v[234:235] op_sel_hi:[1,0]
	v_pk_add_f32 v[138:139], v[138:139], v[234:235] op_sel_hi:[1,0]
	v_pk_add_f32 v[140:141], v[140:141], v[234:235] op_sel_hi:[1,0]
	v_pk_add_f32 v[142:143], v[142:143], v[234:235] op_sel_hi:[1,0]
	v_rcp_f32_e32 v149, v147
	v_add_f32_e32 v146, 1.0, v150
	v_add_f32_e32 v147, 1.0, v151
	v_rcp_f32_e32 v128, v128
	v_rcp_f32_e32 v129, v129
	v_rcp_f32_e32 v130, v130
	v_rcp_f32_e32 v131, v131
	v_rcp_f32_e32 v136, v136
	v_rcp_f32_e32 v137, v137
	v_rcp_f32_e32 v138, v138
	v_rcp_f32_e32 v139, v139
	v_rcp_f32_e32 v140, v140
	v_rcp_f32_e32 v141, v141
	v_rcp_f32_e32 v142, v142
	v_rcp_f32_e32 v143, v143
	v_rcp_f32_e32 v146, v146
	v_rcp_f32_e32 v147, v147
	s_mov_b64 s[4:5], 0
.LBB0_152:
	s_andn2_b64 vcc, exec, s[4:5]
	s_cbranch_vccnz .LBB0_155
	s_waitcnt lgkmcnt(0)
	v_pk_mul_f32 v[130:131], v[14:15], v[134:135] op_sel:[0,1]
	v_pk_mul_f32 v[128:129], v[12:13], v[134:135] op_sel:[0,1]
	v_pk_mul_f32 v[138:139], v[6:7], v[134:135] op_sel:[0,1]
	v_pk_mul_f32 v[136:137], v[4:5], v[134:135] op_sel:[0,1]
	v_pk_mul_f32 v[142:143], v[10:11], v[134:135] op_sel:[0,1]
	v_pk_mul_f32 v[140:141], v[8:9], v[134:135] op_sel:[0,1]
	v_pk_mul_f32 v[146:147], v[2:3], v[134:135] op_sel:[0,1]
	s_cmp_eq_u32 s9, 2
	v_pk_mul_f32 v[148:149], v[0:1], v[134:135] op_sel:[0,1]
	s_cbranch_scc0 .LBB0_155
	v_pk_mul_f32 v[150:151], v[128:129], v[232:233] op_sel_hi:[1,0]
	v_pk_mul_f32 v[152:153], v[130:131], v[232:233] op_sel_hi:[1,0]
	v_exp_f32_e32 v150, v150
	v_exp_f32_e32 v151, v151
	v_exp_f32_e32 v152, v152
	v_exp_f32_e32 v153, v153
	v_pk_add_f32 v[150:151], v[150:151], v[234:235] op_sel_hi:[1,0]
	v_pk_add_f32 v[152:153], v[152:153], v[234:235] op_sel_hi:[1,0]
	v_rcp_f32_e32 v150, v150
	v_rcp_f32_e32 v151, v151
	v_rcp_f32_e32 v152, v152
	v_rcp_f32_e32 v153, v153
	v_pk_mul_f32 v[128:129], v[128:129], v[150:151]
	v_pk_mul_f32 v[150:151], v[136:137], v[232:233] op_sel_hi:[1,0]
	v_pk_mul_f32 v[130:131], v[130:131], v[152:153]
	v_pk_mul_f32 v[152:153], v[138:139], v[232:233] op_sel_hi:[1,0]
	v_exp_f32_e32 v150, v150
	v_exp_f32_e32 v151, v151
	v_exp_f32_e32 v152, v152
	v_exp_f32_e32 v153, v153
	v_pk_add_f32 v[150:151], v[150:151], v[234:235] op_sel_hi:[1,0]
	v_pk_add_f32 v[152:153], v[152:153], v[234:235] op_sel_hi:[1,0]
	v_rcp_f32_e32 v150, v150
	v_rcp_f32_e32 v151, v151
	v_rcp_f32_e32 v152, v152
	v_rcp_f32_e32 v153, v153
	v_pk_mul_f32 v[136:137], v[136:137], v[150:151]
	v_pk_mul_f32 v[150:151], v[140:141], v[232:233] op_sel_hi:[1,0]
	v_pk_mul_f32 v[138:139], v[138:139], v[152:153]
	v_pk_mul_f32 v[152:153], v[142:143], v[232:233] op_sel_hi:[1,0]
	v_exp_f32_e32 v150, v150
	v_exp_f32_e32 v151, v151
	v_exp_f32_e32 v152, v152
	v_exp_f32_e32 v153, v153
	v_pk_add_f32 v[150:151], v[150:151], v[234:235] op_sel_hi:[1,0]
	v_pk_add_f32 v[152:153], v[152:153], v[234:235] op_sel_hi:[1,0]
	v_rcp_f32_e32 v150, v150
	v_rcp_f32_e32 v151, v151
	v_rcp_f32_e32 v152, v152
	v_rcp_f32_e32 v153, v153
	v_pk_mul_f32 v[140:141], v[140:141], v[150:151]
	v_pk_mul_f32 v[150:151], v[148:149], v[232:233] op_sel_hi:[1,0]
	v_pk_mul_f32 v[142:143], v[142:143], v[152:153]
	v_pk_mul_f32 v[152:153], v[146:147], v[232:233] op_sel_hi:[1,0]
	v_exp_f32_e32 v150, v150
	v_exp_f32_e32 v151, v151
	v_exp_f32_e32 v152, v152
	v_exp_f32_e32 v153, v153
	v_pk_add_f32 v[150:151], v[150:151], v[234:235] op_sel_hi:[1,0]
	v_pk_add_f32 v[152:153], v[152:153], v[234:235] op_sel_hi:[1,0]
	v_rcp_f32_e32 v150, v150
	v_rcp_f32_e32 v151, v151
	v_rcp_f32_e32 v152, v152
	v_rcp_f32_e32 v153, v153
	v_pk_mul_f32 v[148:149], v[148:149], v[150:151]
	v_pk_mul_f32 v[146:147], v[146:147], v[152:153]
